# int8 loops: alternate chains issue k-steps in opposite order so consecutive MFMAs share SrcA exactly (integer accumulate, identical results)
# speedup vs baseline: 1.0137x; 1.0017x over previous
; #define PG8_STAGE(bufoff, gbase, voff) do { _Pragma("unroll") for (int _i = 0; _i < 2; ++_i) \
;         __builtin_amdgcn_global_load_lds((const unsigned*)((const char*)(gbase) + (voff)[_i]), (PG8_LAS unsigned*)(lds + (bufoff) + ldsw + _i * 8192), 16, 0, 0); } while (0)
; #define PG8_LDA(dst, b, h) do { _Pragma("unroll") for (int m = 0; m < 4; ++m) _Pragma("unroll") for (int k = 0; k < 2; ++k) dst[m][k] = *(const PG8_LAS bf16x8*)(lds + PG8_SA(b, h) + aoff + m * 2048 + k * 1024); } while (0)
; #define PG8_LDB(dst, b, h) do { _Pragma("unroll") for (int n = 0; n < 2; ++n) _Pragma("unroll") for (int k = 0; k < 2; ++k) dst[n][k] = *(const PG8_LAS bf16x8*)(lds + PG8_SB(b, h) + boff + n * 2048 + k * 1024); } while (0)
; #define PG8_WAIT_V(n) asm volatile("s_waitcnt vmcnt(" #n ")" ::: "memory")
; #define PG8_WAIT_L(n) asm volatile("s_waitcnt lgkmcnt(" #n ")" ::: "memory")
; #define PG8_BAR __builtin_amdgcn_s_barrier()
; #define PG8_SCHED __builtin_amdgcn_sched_barrier(0)
; template <class Epi, class Sched, bool ALIGN_EPI = false, bool SP2 = false, bool I8 = false>
; __device__ __forceinline__ void gemm_phase(PG8_LAS unsigned char* lds, const Gemm g, const Sched& S, const Epi& E) {
;     ...
;         const bool has_next = S.next(ui + 1, nxt);
;         const char* nA = has_next ? (const char*)g.A + (size_t)nxt.pm * tstep : cA; const char* nB = has_next ? (const char*)g.Bt + (size_t)nxt.pn * tstep : cB;
;         for (int t = 0; t < nt; t += 2) {
;             const bool last = (t == nt - 2);
;             const char* a1 = cA + (size_t)(t + 1) * kstep;
;             const char* a2 = last ? nA : cA + (size_t)(t + 2) * kstep; const char* b2 = last ? nB : cB + (size_t)(t + 2) * kstep;
;             const char* a3 = a2 + kstep; const char* b3 = b2 + kstep;
;             if (last && has_next) S.a_ready(nxt);
;             if constexpr (SP2) {
;             PG8_LDB(B0, 0, 0); PG8_LDB(B1, 0, 1); PG8_SCHED; PG8_LDA(At, 0, 0); PG8_STAGE(PG8_SA(1, 1), a1 + hstep, voffA);
;             PG8_WAIT_V(8); PG8_WAIT_L(0); PG8_BAR; PG8_MMA(0, 0, At, B0); PG8_MMA(0, 1, At, B1); PG8_BAR; PG8_SCHED;
;             PG8_LDA(At, 0, 1); PG8_STAGE(PG8_SB(0, 0), b2, voffB); PG8_STAGE(PG8_SB(0, 1), b2 + hstep, voffB); PG8_STAGE(PG8_SA(0, 0), a2, voffA);
.LBB0_207:
	s_ashr_i32 s19, s18, 31
	s_lshl_b64 s[22:23], s[18:19], 20
	s_add_u32 s22, s28, s22
	s_addc_u32 s23, s34, s23
	s_and_b64 s[24:25], s[6:7], exec
	s_cselect_b32 s19, s23, s27
	s_cselect_b32 s64, s22, s26
	s_ashr_i32 s17, s16, 31
	s_lshl_b64 s[24:25], s[16:17], 20
	s_add_u32 s24, s35, s24
	s_addc_u32 s25, s42, s25
	s_and_b64 s[40:41], s[6:7], exec
	s_cselect_b32 s17, s25, s37
	s_cselect_b32 s65, s24, s36
	s_add_u32 s26, s26, 0x80080
	s_addc_u32 s27, s27, 0
	s_add_u32 s72, s36, 0x100
	s_addc_u32 s73, s37, 0
	s_mov_b32 s76, -2
	s_add_u32 s36, s26, 0xfff80080
	s_addc_u32 s37, s27, -1
	s_add_i32 s50, 0, 0x10000
	s_cmp_eq_u32 s76, 28
	s_cselect_b32 s41, s19, s37
	s_cselect_b32 s40, s64, s36
	s_cselect_b32 s37, s17, s73
	s_cselect_b32 s36, s65, s72
	s_add_i32 s56, 0, 0x14000
	v_add_u32_e32 v136, s50, v175
	v_add_u32_e32 v172, s56, v175
	ds_read_b128 v[116:119], v136
	ds_read_b128 v[124:127], v136 offset:1024
	ds_read_b128 v[132:135], v136 offset:2048
	ds_read_b128 v[136:139], v136 offset:3072
	ds_read_b128 v[160:163], v172
	ds_read_b128 v[164:167], v172 offset:1024
	ds_read_b128 v[168:171], v172 offset:2048
	ds_read_b128 v[178:181], v172 offset:3072
	v_lshl_add_u64 v[172:173], s[26:27], 0, v[156:157]
	s_add_i32 m0, s44, 0xc000
	ds_read_b128 v[182:185], v177
	ds_read_b128 v[186:189], v177 offset:1024
	ds_read_b128 v[204:207], v177 offset:2048
	ds_read_b128 v[208:211], v177 offset:3072
	ds_read_b128 v[212:215], v177 offset:4096
	ds_read_b128 v[216:219], v177 offset:5120
	ds_read_b128 v[220:223], v177 offset:6144
	ds_read_b128 v[224:227], v177 offset:7168
	global_load_lds_dwordx4 v[172:173], off
	v_lshl_add_u64 v[172:173], s[26:27], 0, v[158:159]
	s_add_i32 m0, s44, 0xe000
	s_nop 0
	global_load_lds_dwordx4 v[172:173], off
	s_waitcnt vmcnt(8)
	s_waitcnt lgkmcnt(0)
	s_barrier
	s_setprio 1
	s_waitcnt lgkmcnt(0)
	v_mfma_i32_16x16x64_i8 v[144:147], v[116:119], v[182:185], 0
	v_mfma_i32_16x16x64_i8 v[144:147], v[124:127], v[186:189], v[144:147]
	v_mfma_i32_16x16x64_i8 v[112:115], v[124:127], v[208:211], 0
	v_mfma_i32_16x16x64_i8 v[112:115], v[116:119], v[204:207], v[112:115]
	v_mfma_i32_16x16x64_i8 v[96:99], v[116:119], v[212:215], 0
	v_mfma_i32_16x16x64_i8 v[96:99], v[124:127], v[216:219], v[96:99]
	v_mfma_i32_16x16x64_i8 v[80:83], v[124:127], v[224:227], 0
	v_mfma_i32_16x16x64_i8 v[80:83], v[116:119], v[220:223], v[80:83]
	v_mfma_i32_16x16x64_i8 v[140:143], v[132:135], v[182:185], 0
	v_mfma_i32_16x16x64_i8 v[140:143], v[136:139], v[186:189], v[140:143]
	v_mfma_i32_16x16x64_i8 v[108:111], v[136:139], v[208:211], 0
	v_mfma_i32_16x16x64_i8 v[108:111], v[132:135], v[204:207], v[108:111]
	v_mfma_i32_16x16x64_i8 v[92:95], v[132:135], v[212:215], 0
	v_mfma_i32_16x16x64_i8 v[92:95], v[136:139], v[216:219], v[92:95]
	v_mfma_i32_16x16x64_i8 v[76:79], v[136:139], v[224:227], 0
	v_mfma_i32_16x16x64_i8 v[76:79], v[132:135], v[220:223], v[76:79]
	s_setprio 0
	s_setprio 1
	v_mfma_i32_16x16x64_i8 v[128:131], v[160:163], v[182:185], 0
	v_mfma_i32_16x16x64_i8 v[128:131], v[164:167], v[186:189], v[128:131]
	v_mfma_i32_16x16x64_i8 v[104:107], v[164:167], v[208:211], 0
	v_mfma_i32_16x16x64_i8 v[104:107], v[160:163], v[204:207], v[104:107]
	v_mfma_i32_16x16x64_i8 v[88:91], v[160:163], v[212:215], 0
	v_mfma_i32_16x16x64_i8 v[88:91], v[164:167], v[216:219], v[88:91]
	v_mfma_i32_16x16x64_i8 v[72:75], v[164:167], v[224:227], 0
	v_mfma_i32_16x16x64_i8 v[72:75], v[160:163], v[220:223], v[72:75]
	v_mfma_i32_16x16x64_i8 v[120:123], v[168:171], v[182:185], 0
	v_mfma_i32_16x16x64_i8 v[120:123], v[178:181], v[186:189], v[120:123]
	v_mfma_i32_16x16x64_i8 v[100:103], v[178:181], v[208:211], 0
	v_mfma_i32_16x16x64_i8 v[100:103], v[168:171], v[204:207], v[100:103]
	v_mfma_i32_16x16x64_i8 v[84:87], v[168:171], v[212:215], 0
	v_mfma_i32_16x16x64_i8 v[84:87], v[178:181], v[216:219], v[84:87]
	v_mfma_i32_16x16x64_i8 v[68:71], v[178:181], v[224:227], 0
	v_mfma_i32_16x16x64_i8 v[68:71], v[168:171], v[220:223], v[68:71]
	s_setprio 0
	s_barrier
	s_add_i32 s50, s50, s43
	v_lshl_add_u64 v[172:173], s[36:37], 0, v[2:3]
	s_mov_b32 m0, s50
	ds_read_b128 v[182:185], v177 offset:16384
	ds_read_b128 v[186:189], v177 offset:17408
	ds_read_b128 v[204:207], v177 offset:18432
	ds_read_b128 v[208:211], v177 offset:19456
	ds_read_b128 v[212:215], v177 offset:20480
	ds_read_b128 v[216:219], v177 offset:21504
	ds_read_b128 v[220:223], v177 offset:22528
	ds_read_b128 v[224:227], v177 offset:23552
	global_load_lds_dwordx4 v[172:173], off
	s_add_i32 m0, s50, 0x2000
	s_add_u32 s50, s36, 0x80000
	v_lshl_add_u64 v[190:191], s[36:37], 0, v[148:149]
	s_addc_u32 s51, s37, 0
	s_add_i32 s56, s56, s43
	global_load_lds_dwordx4 v[190:191], off
	v_lshl_add_u64 v[228:229], s[50:51], 0, v[2:3]
	s_mov_b32 m0, s56
	v_lshl_add_u64 v[240:241], s[40:41], 0, v[150:151]
	global_load_lds_dwordx4 v[228:229], off
	v_lshl_add_u64 v[228:229], s[50:51], 0, v[148:149]
	s_add_i32 m0, s56, 0x2000
	s_nop 0
	global_load_lds_dwordx4 v[228:229], off
	v_lshl_add_u64 v[228:229], s[40:41], 0, v[152:153]
	s_mov_b32 m0, s44
	s_nop 0
	global_load_lds_dwordx4 v[228:229], off
	s_mov_b32 m0, s45
	s_nop 0
	global_load_lds_dwordx4 v[240:241], off
	s_waitcnt vmcnt(8)
	s_waitcnt lgkmcnt(0)
	s_barrier
; #define PG8_STAGE(bufoff, gbase, voff) do { _Pragma("unroll") for (int _i = 0; _i < 2; ++_i) \
;         __builtin_amdgcn_global_load_lds((const unsigned*)((const char*)(gbase) + (voff)[_i]), (PG8_LAS unsigned*)(lds + (bufoff) + ldsw + _i * 8192), 16, 0, 0); } while (0)
; #define PG8_LDA(dst, b, h) do { _Pragma("unroll") for (int m = 0; m < 4; ++m) _Pragma("unroll") for (int k = 0; k < 2; ++k) dst[m][k] = *(const PG8_LAS bf16x8*)(lds + PG8_SA(b, h) + aoff + m * 2048 + k * 1024); } while (0)
; #define PG8_LDB(dst, b, h) do { _Pragma("unroll") for (int n = 0; n < 2; ++n) _Pragma("unroll") for (int k = 0; k < 2; ++k) dst[n][k] = *(const PG8_LAS bf16x8*)(lds + PG8_SB(b, h) + boff + n * 2048 + k * 1024); } while (0)
; #define PG8_WAIT_V(n) asm volatile("s_waitcnt vmcnt(" #n ")" ::: "memory")
; #define PG8_WAIT_L(n) asm volatile("s_waitcnt lgkmcnt(" #n ")" ::: "memory")
; #define PG8_BAR __builtin_amdgcn_s_barrier()
; #define PG8_SCHED __builtin_amdgcn_sched_barrier(0)
; template <class Epi, class Sched, bool ALIGN_EPI = false, bool SP2 = false, bool I8 = false>
; __device__ __forceinline__ void gemm_phase(PG8_LAS unsigned char* lds, const Gemm g, const Sched& S, const Epi& E) {
;     ...
;             PG8_WAIT_V(8); PG8_WAIT_L(0); PG8_BAR; PG8_MMA(1, 0, At, B0); PG8_MMA(1, 1, At, B1); PG8_BAR; PG8_SCHED;
;             PG8_LDB(B0, 1, 0); PG8_LDB(B1, 1, 1); PG8_SCHED; PG8_LDA(At, 1, 0); PG8_STAGE(PG8_SA(0, 1), a2 + hstep, voffA);
;             PG8_WAIT_V(8); PG8_WAIT_L(0); PG8_BAR; PG8_MMA(0, 0, At, B0); PG8_MMA(0, 1, At, B1); PG8_BAR; PG8_SCHED;
	s_setprio 1
	s_waitcnt lgkmcnt(0)
	v_mfma_i32_16x16x64_i8 v[64:67], v[116:119], v[182:185], 0
	v_mfma_i32_16x16x64_i8 v[64:67], v[124:127], v[186:189], v[64:67]
	v_mfma_i32_16x16x64_i8 v[48:51], v[124:127], v[208:211], 0
	v_mfma_i32_16x16x64_i8 v[48:51], v[116:119], v[204:207], v[48:51]
	v_mfma_i32_16x16x64_i8 v[32:35], v[116:119], v[212:215], 0
	v_mfma_i32_16x16x64_i8 v[32:35], v[124:127], v[216:219], v[32:35]
	v_mfma_i32_16x16x64_i8 v[16:19], v[124:127], v[224:227], 0
	v_mfma_i32_16x16x64_i8 v[16:19], v[116:119], v[220:223], v[16:19]
	v_mfma_i32_16x16x64_i8 v[60:63], v[132:135], v[182:185], 0
	v_mfma_i32_16x16x64_i8 v[60:63], v[136:139], v[186:189], v[60:63]
	v_mfma_i32_16x16x64_i8 v[44:47], v[136:139], v[208:211], 0
	v_mfma_i32_16x16x64_i8 v[44:47], v[132:135], v[204:207], v[44:47]
	v_mfma_i32_16x16x64_i8 v[28:31], v[132:135], v[212:215], 0
	v_mfma_i32_16x16x64_i8 v[28:31], v[136:139], v[216:219], v[28:31]
	v_mfma_i32_16x16x64_i8 v[12:15], v[136:139], v[224:227], 0
	v_mfma_i32_16x16x64_i8 v[12:15], v[132:135], v[220:223], v[12:15]
	s_setprio 0
	s_setprio 1
	v_mfma_i32_16x16x64_i8 v[56:59], v[160:163], v[182:185], 0
	v_mfma_i32_16x16x64_i8 v[56:59], v[164:167], v[186:189], v[56:59]
	v_mfma_i32_16x16x64_i8 v[40:43], v[164:167], v[208:211], 0
	v_mfma_i32_16x16x64_i8 v[40:43], v[160:163], v[204:207], v[40:43]
	v_mfma_i32_16x16x64_i8 v[24:27], v[160:163], v[212:215], 0
	v_mfma_i32_16x16x64_i8 v[24:27], v[164:167], v[216:219], v[24:27]
	v_mfma_i32_16x16x64_i8 v[8:11], v[164:167], v[224:227], 0
	v_mfma_i32_16x16x64_i8 v[8:11], v[160:163], v[220:223], v[8:11]
	v_mfma_i32_16x16x64_i8 v[52:55], v[168:171], v[182:185], 0
	v_mfma_i32_16x16x64_i8 v[52:55], v[178:181], v[186:189], v[52:55]
	v_mfma_i32_16x16x64_i8 v[36:39], v[178:181], v[208:211], 0
	v_mfma_i32_16x16x64_i8 v[36:39], v[168:171], v[204:207], v[36:39]
	v_mfma_i32_16x16x64_i8 v[20:23], v[168:171], v[212:215], 0
	v_mfma_i32_16x16x64_i8 v[20:23], v[178:181], v[216:219], v[20:23]
	v_mfma_i32_16x16x64_i8 v[4:7], v[178:181], v[224:227], 0
	v_mfma_i32_16x16x64_i8 v[4:7], v[168:171], v[220:223], v[4:7]
	s_setprio 0
	s_barrier
	s_add_i32 s50, 0, 0x18000
	s_add_i32 s51, 0, 0x1c000
	v_add_u32_e32 v136, s50, v175
	v_add_u32_e32 v178, s51, v175
	ds_read_b128 v[116:119], v136
	ds_read_b128 v[124:127], v136 offset:1024
	ds_read_b128 v[132:135], v136 offset:2048
	ds_read_b128 v[136:139], v136 offset:3072
	ds_read_b128 v[160:163], v178
	ds_read_b128 v[164:167], v178 offset:1024
	ds_read_b128 v[168:171], v178 offset:2048
	ds_read_b128 v[178:181], v178 offset:3072
	s_add_u32 s40, s40, 0x80000
	s_addc_u32 s41, s41, 0
	s_mov_b32 m0, s46
	v_lshl_add_u64 v[242:243], s[40:41], 0, v[152:153]
	ds_read_b128 v[182:185], v177 offset:32768
	ds_read_b128 v[186:189], v177 offset:33792
	ds_read_b128 v[204:207], v177 offset:34816
	ds_read_b128 v[208:211], v177 offset:35840
	ds_read_b128 v[212:215], v177 offset:36864
	ds_read_b128 v[216:219], v177 offset:37888
	ds_read_b128 v[220:223], v177 offset:38912
	ds_read_b128 v[224:227], v177 offset:39936
	global_load_lds_dwordx4 v[242:243], off
	v_lshl_add_u64 v[242:243], s[40:41], 0, v[150:151]
	s_mov_b32 m0, s47
	s_nop 0
	global_load_lds_dwordx4 v[242:243], off
	s_waitcnt vmcnt(8)
	s_waitcnt lgkmcnt(0)
	s_barrier
	s_setprio 1
	s_waitcnt lgkmcnt(0)
	v_mfma_i32_16x16x64_i8 v[144:147], v[116:119], v[182:185], v[144:147]
	v_mfma_i32_16x16x64_i8 v[144:147], v[124:127], v[186:189], v[144:147]
	v_mfma_i32_16x16x64_i8 v[112:115], v[124:127], v[208:211], v[112:115]
	v_mfma_i32_16x16x64_i8 v[112:115], v[116:119], v[204:207], v[112:115]
	v_mfma_i32_16x16x64_i8 v[96:99], v[116:119], v[212:215], v[96:99]
	v_mfma_i32_16x16x64_i8 v[96:99], v[124:127], v[216:219], v[96:99]
	v_mfma_i32_16x16x64_i8 v[80:83], v[124:127], v[224:227], v[80:83]
	v_mfma_i32_16x16x64_i8 v[80:83], v[116:119], v[220:223], v[80:83]
	v_mfma_i32_16x16x64_i8 v[140:143], v[132:135], v[182:185], v[140:143]
	v_mfma_i32_16x16x64_i8 v[140:143], v[136:139], v[186:189], v[140:143]
	v_mfma_i32_16x16x64_i8 v[108:111], v[136:139], v[208:211], v[108:111]
	v_mfma_i32_16x16x64_i8 v[108:111], v[132:135], v[204:207], v[108:111]
	v_mfma_i32_16x16x64_i8 v[92:95], v[132:135], v[212:215], v[92:95]
	v_mfma_i32_16x16x64_i8 v[92:95], v[136:139], v[216:219], v[92:95]
	v_mfma_i32_16x16x64_i8 v[76:79], v[136:139], v[224:227], v[76:79]
	v_mfma_i32_16x16x64_i8 v[76:79], v[132:135], v[220:223], v[76:79]
	s_setprio 0
	s_setprio 1
	v_mfma_i32_16x16x64_i8 v[128:131], v[160:163], v[182:185], v[128:131]
	v_mfma_i32_16x16x64_i8 v[128:131], v[164:167], v[186:189], v[128:131]
	v_mfma_i32_16x16x64_i8 v[104:107], v[164:167], v[208:211], v[104:107]
	v_mfma_i32_16x16x64_i8 v[104:107], v[160:163], v[204:207], v[104:107]
	v_mfma_i32_16x16x64_i8 v[88:91], v[160:163], v[212:215], v[88:91]
	v_mfma_i32_16x16x64_i8 v[88:91], v[164:167], v[216:219], v[88:91]
	v_mfma_i32_16x16x64_i8 v[72:75], v[164:167], v[224:227], v[72:75]
	v_mfma_i32_16x16x64_i8 v[72:75], v[160:163], v[220:223], v[72:75]
	v_mfma_i32_16x16x64_i8 v[120:123], v[168:171], v[182:185], v[120:123]
	v_mfma_i32_16x16x64_i8 v[120:123], v[178:181], v[186:189], v[120:123]
	v_mfma_i32_16x16x64_i8 v[100:103], v[178:181], v[208:211], v[100:103]
	v_mfma_i32_16x16x64_i8 v[100:103], v[168:171], v[204:207], v[100:103]
	v_mfma_i32_16x16x64_i8 v[84:87], v[168:171], v[212:215], v[84:87]
	v_mfma_i32_16x16x64_i8 v[84:87], v[178:181], v[216:219], v[84:87]
	v_mfma_i32_16x16x64_i8 v[68:71], v[178:181], v[224:227], v[68:71]
	v_mfma_i32_16x16x64_i8 v[68:71], v[168:171], v[220:223], v[68:71]
	s_setprio 0
	s_barrier
; #define PG8_STAGE(bufoff, gbase, voff) do { _Pragma("unroll") for (int _i = 0; _i < 2; ++_i) \
;         __builtin_amdgcn_global_load_lds((const unsigned*)((const char*)(gbase) + (voff)[_i]), (PG8_LAS unsigned*)(lds + (bufoff) + ldsw + _i * 8192), 16, 0, 0); } while (0)
; #define PG8_LDA(dst, b, h) do { _Pragma("unroll") for (int m = 0; m < 4; ++m) _Pragma("unroll") for (int k = 0; k < 2; ++k) dst[m][k] = *(const PG8_LAS bf16x8*)(lds + PG8_SA(b, h) + aoff + m * 2048 + k * 1024); } while (0)
; #define PG8_WAIT_V(n) asm volatile("s_waitcnt vmcnt(" #n ")" ::: "memory")
; #define PG8_WAIT_L(n) asm volatile("s_waitcnt lgkmcnt(" #n ")" ::: "memory")
; #define PG8_BAR __builtin_amdgcn_s_barrier()
; template <class Epi, class Sched, bool ALIGN_EPI = false, bool SP2 = false, bool I8 = false>
; __device__ __forceinline__ void gemm_phase(PG8_LAS unsigned char* lds, const Gemm g, const Sched& S, const Epi& E) {
;     ...
;         for (int t = 0; t < nt; t += 2) {
;             const bool last = (t == nt - 2);
;             const char* a1 = cA + (size_t)(t + 1) * kstep;
;             const char* a2 = last ? nA : cA + (size_t)(t + 2) * kstep; const char* b2 = last ? nB : cB + (size_t)(t + 2) * kstep;
;             const char* a3 = a2 + kstep; const char* b3 = b2 + kstep;
;             if (last && has_next) S.a_ready(nxt);
;             if constexpr (SP2) {
;             PG8_LDB(B0, 0, 0); PG8_LDB(B1, 0, 1); PG8_SCHED; PG8_LDA(At, 0, 0); PG8_STAGE(PG8_SA(1, 1), a1 + hstep, voffA);
;             PG8_WAIT_V(8); PG8_WAIT_L(0); PG8_BAR; PG8_MMA(0, 0, At, B0); PG8_MMA(0, 1, At, B1); PG8_BAR; PG8_SCHED;
;             PG8_LDA(At, 0, 1); PG8_STAGE(PG8_SB(0, 0), b2, voffB); PG8_STAGE(PG8_SB(0, 1), b2 + hstep, voffB); PG8_STAGE(PG8_SA(0, 0), a2, voffA);
;             PG8_WAIT_V(8); PG8_WAIT_L(0); PG8_BAR; PG8_MMA(1, 0, At, B0); PG8_MMA(1, 1, At, B1); PG8_BAR; PG8_SCHED;
;             PG8_LDB(B0, 1, 0); PG8_LDB(B1, 1, 1); PG8_SCHED; PG8_LDA(At, 1, 0); PG8_STAGE(PG8_SA(0, 1), a2 + hstep, voffA);
;             PG8_WAIT_V(8); PG8_WAIT_L(0); PG8_BAR; PG8_MMA(0, 0, At, B0); PG8_MMA(0, 1, At, B1); PG8_BAR; PG8_SCHED;
;             PG8_LDA(At, 1, 1); PG8_STAGE(PG8_SB(1, 0), b3, voffB); PG8_STAGE(PG8_SB(1, 1), b3 + hstep, voffB); PG8_STAGE(PG8_SA(1, 0), a3, voffA);
;             PG8_WAIT_V(8); PG8_WAIT_L(0); PG8_BAR; PG8_MMA(1, 0, At, B0); PG8_MMA(1, 1, At, B1); PG8_BAR; PG8_SCHED;
	s_add_i32 s40, s50, s43
	v_lshl_add_u64 v[172:173], v[172:173], 0, s[84:85]
	s_mov_b32 m0, s40
	ds_read_b128 v[182:185], v177 offset:49152
	ds_read_b128 v[186:189], v177 offset:50176
	ds_read_b128 v[204:207], v177 offset:51200
	ds_read_b128 v[208:211], v177 offset:52224
	ds_read_b128 v[212:215], v177 offset:53248
	ds_read_b128 v[216:219], v177 offset:54272
	ds_read_b128 v[220:223], v177 offset:55296
	ds_read_b128 v[224:227], v177 offset:56320
	global_load_lds_dwordx4 v[172:173], off
	s_add_i32 m0, s40, 0x2000
	s_add_u32 s36, s36, 0x80080
	v_lshl_add_u64 v[172:173], v[190:191], 0, s[84:85]
	s_addc_u32 s37, s37, 0
	s_add_i32 s40, s51, s43
	global_load_lds_dwordx4 v[172:173], off
	v_lshl_add_u64 v[172:173], s[36:37], 0, v[2:3]
	s_mov_b32 m0, s40
	s_nop 0
	global_load_lds_dwordx4 v[172:173], off
	v_lshl_add_u64 v[172:173], s[36:37], 0, v[148:149]
	s_add_i32 m0, s40, 0x2000
	s_nop 0
	global_load_lds_dwordx4 v[172:173], off
	v_lshl_add_u64 v[172:173], v[228:229], 0, s[84:85]
	s_mov_b32 m0, s52
	s_nop 0
	global_load_lds_dwordx4 v[172:173], off
	v_lshl_add_u64 v[172:173], v[240:241], 0, s[84:85]
	s_mov_b32 m0, s53
	s_nop 0
	global_load_lds_dwordx4 v[172:173], off
	s_waitcnt vmcnt(8)
	s_waitcnt lgkmcnt(0)
	s_barrier
	s_setprio 1
	s_waitcnt lgkmcnt(0)
	v_mfma_i32_16x16x64_i8 v[64:67], v[116:119], v[182:185], v[64:67]
	v_mfma_i32_16x16x64_i8 v[64:67], v[124:127], v[186:189], v[64:67]
	v_mfma_i32_16x16x64_i8 v[48:51], v[124:127], v[208:211], v[48:51]
	v_mfma_i32_16x16x64_i8 v[48:51], v[116:119], v[204:207], v[48:51]
	v_mfma_i32_16x16x64_i8 v[32:35], v[116:119], v[212:215], v[32:35]
	v_mfma_i32_16x16x64_i8 v[32:35], v[124:127], v[216:219], v[32:35]
	v_mfma_i32_16x16x64_i8 v[16:19], v[124:127], v[224:227], v[16:19]
	v_mfma_i32_16x16x64_i8 v[16:19], v[116:119], v[220:223], v[16:19]
	v_mfma_i32_16x16x64_i8 v[60:63], v[132:135], v[182:185], v[60:63]
	v_mfma_i32_16x16x64_i8 v[60:63], v[136:139], v[186:189], v[60:63]
	v_mfma_i32_16x16x64_i8 v[44:47], v[136:139], v[208:211], v[44:47]
	v_mfma_i32_16x16x64_i8 v[44:47], v[132:135], v[204:207], v[44:47]
	v_mfma_i32_16x16x64_i8 v[28:31], v[132:135], v[212:215], v[28:31]
	v_mfma_i32_16x16x64_i8 v[28:31], v[136:139], v[216:219], v[28:31]
	v_mfma_i32_16x16x64_i8 v[12:15], v[136:139], v[224:227], v[12:15]
	v_mfma_i32_16x16x64_i8 v[12:15], v[132:135], v[220:223], v[12:15]
	s_setprio 0
	s_setprio 1
	v_mfma_i32_16x16x64_i8 v[56:59], v[160:163], v[182:185], v[56:59]
	v_mfma_i32_16x16x64_i8 v[56:59], v[164:167], v[186:189], v[56:59]
	v_mfma_i32_16x16x64_i8 v[40:43], v[164:167], v[208:211], v[40:43]
	v_mfma_i32_16x16x64_i8 v[40:43], v[160:163], v[204:207], v[40:43]
	v_mfma_i32_16x16x64_i8 v[24:27], v[160:163], v[212:215], v[24:27]
	v_mfma_i32_16x16x64_i8 v[24:27], v[164:167], v[216:219], v[24:27]
	v_mfma_i32_16x16x64_i8 v[8:11], v[164:167], v[224:227], v[8:11]
	v_mfma_i32_16x16x64_i8 v[8:11], v[160:163], v[220:223], v[8:11]
	v_mfma_i32_16x16x64_i8 v[52:55], v[168:171], v[182:185], v[52:55]
	v_mfma_i32_16x16x64_i8 v[52:55], v[178:181], v[186:189], v[52:55]
	v_mfma_i32_16x16x64_i8 v[36:39], v[178:181], v[208:211], v[36:39]
	v_mfma_i32_16x16x64_i8 v[36:39], v[168:171], v[204:207], v[36:39]
	v_mfma_i32_16x16x64_i8 v[20:23], v[168:171], v[212:215], v[20:23]
	v_mfma_i32_16x16x64_i8 v[20:23], v[178:181], v[216:219], v[20:23]
	v_mfma_i32_16x16x64_i8 v[4:7], v[178:181], v[224:227], v[4:7]
	v_mfma_i32_16x16x64_i8 v[4:7], v[168:171], v[220:223], v[4:7]
	s_setprio 0
	s_barrier
	s_add_i32 s76, s76, 2
	s_add_u32 s26, s26, 0x100
	s_addc_u32 s27, s27, 0
	s_add_u32 s72, s72, 0x100
	s_addc_u32 s73, s73, 0
	s_cmp_gt_u32 s76, 29
	s_cbranch_scc1 .Lkloop_exit_0
.LBB0_208:
	s_add_u32 s36, s26, 0xfff80080
	s_addc_u32 s37, s27, -1
	s_add_i32 s50, 0, 0x10000
	s_cmp_eq_u32 s76, 28
	s_cselect_b32 s41, s19, s37
	s_cselect_b32 s40, s64, s36
	s_cselect_b32 s37, s17, s73
	s_cselect_b32 s36, s65, s72
	s_add_i32 s56, 0, 0x14000
	v_add_u32_e32 v136, s50, v175
	v_add_u32_e32 v172, s56, v175
	ds_read_b128 v[116:119], v136
	ds_read_b128 v[124:127], v136 offset:1024
	ds_read_b128 v[132:135], v136 offset:2048
	ds_read_b128 v[136:139], v136 offset:3072
	ds_read_b128 v[160:163], v172
	ds_read_b128 v[164:167], v172 offset:1024
	ds_read_b128 v[168:171], v172 offset:2048
	ds_read_b128 v[178:181], v172 offset:3072
	v_lshl_add_u64 v[172:173], s[26:27], 0, v[156:157]
	s_add_i32 m0, s44, 0xc000
	ds_read_b128 v[182:185], v177
	ds_read_b128 v[186:189], v177 offset:1024
	ds_read_b128 v[204:207], v177 offset:2048
	ds_read_b128 v[208:211], v177 offset:3072
	ds_read_b128 v[212:215], v177 offset:4096
	ds_read_b128 v[216:219], v177 offset:5120
	ds_read_b128 v[220:223], v177 offset:6144
	ds_read_b128 v[224:227], v177 offset:7168
	global_load_lds_dwordx4 v[172:173], off
	v_lshl_add_u64 v[172:173], s[26:27], 0, v[158:159]
	s_add_i32 m0, s44, 0xe000
	s_nop 0
	global_load_lds_dwordx4 v[172:173], off
	s_waitcnt vmcnt(8)
	s_waitcnt lgkmcnt(0)
	s_barrier
; #define PG8_STAGE(bufoff, gbase, voff) do { _Pragma("unroll") for (int _i = 0; _i < 2; ++_i) \
;         __builtin_amdgcn_global_load_lds((const unsigned*)((const char*)(gbase) + (voff)[_i]), (PG8_LAS unsigned*)(lds + (bufoff) + ldsw + _i * 8192), 16, 0, 0); } while (0)
; #define PG8_LDA(dst, b, h) do { _Pragma("unroll") for (int m = 0; m < 4; ++m) _Pragma("unroll") for (int k = 0; k < 2; ++k) dst[m][k] = *(const PG8_LAS bf16x8*)(lds + PG8_SA(b, h) + aoff + m * 2048 + k * 1024); } while (0)
; #define PG8_WAIT_V(n) asm volatile("s_waitcnt vmcnt(" #n ")" ::: "memory")
; #define PG8_WAIT_L(n) asm volatile("s_waitcnt lgkmcnt(" #n ")" ::: "memory")
; #define PG8_BAR __builtin_amdgcn_s_barrier()
; #define PG8_SCHED __builtin_amdgcn_sched_barrier(0)
; template <class Epi, class Sched, bool ALIGN_EPI = false, bool SP2 = false, bool I8 = false>
; __device__ __forceinline__ void gemm_phase(PG8_LAS unsigned char* lds, const Gemm g, const Sched& S, const Epi& E) {
;     ...
;             PG8_WAIT_V(8); PG8_WAIT_L(0); PG8_BAR; PG8_MMA(0, 0, At, B0); PG8_MMA(0, 1, At, B1); PG8_BAR; PG8_SCHED;
;             PG8_LDA(At, 0, 1); PG8_STAGE(PG8_SB(0, 0), b2, voffB); PG8_STAGE(PG8_SB(0, 1), b2 + hstep, voffB); PG8_STAGE(PG8_SA(0, 0), a2, voffA);
;             PG8_WAIT_V(8); PG8_WAIT_L(0); PG8_BAR; PG8_MMA(1, 0, At, B0); PG8_MMA(1, 1, At, B1); PG8_BAR; PG8_SCHED;
	s_setprio 1
	s_waitcnt lgkmcnt(0)
	v_mfma_i32_16x16x64_i8 v[144:147], v[116:119], v[182:185], v[144:147]
	v_mfma_i32_16x16x64_i8 v[144:147], v[124:127], v[186:189], v[144:147]
	v_mfma_i32_16x16x64_i8 v[112:115], v[124:127], v[208:211], v[112:115]
	v_mfma_i32_16x16x64_i8 v[112:115], v[116:119], v[204:207], v[112:115]
	v_mfma_i32_16x16x64_i8 v[96:99], v[116:119], v[212:215], v[96:99]
	v_mfma_i32_16x16x64_i8 v[96:99], v[124:127], v[216:219], v[96:99]
	v_mfma_i32_16x16x64_i8 v[80:83], v[124:127], v[224:227], v[80:83]
	v_mfma_i32_16x16x64_i8 v[80:83], v[116:119], v[220:223], v[80:83]
	v_mfma_i32_16x16x64_i8 v[140:143], v[132:135], v[182:185], v[140:143]
	v_mfma_i32_16x16x64_i8 v[140:143], v[136:139], v[186:189], v[140:143]
	v_mfma_i32_16x16x64_i8 v[108:111], v[136:139], v[208:211], v[108:111]
	v_mfma_i32_16x16x64_i8 v[108:111], v[132:135], v[204:207], v[108:111]
	v_mfma_i32_16x16x64_i8 v[92:95], v[132:135], v[212:215], v[92:95]
	v_mfma_i32_16x16x64_i8 v[92:95], v[136:139], v[216:219], v[92:95]
	v_mfma_i32_16x16x64_i8 v[76:79], v[136:139], v[224:227], v[76:79]
	v_mfma_i32_16x16x64_i8 v[76:79], v[132:135], v[220:223], v[76:79]
	s_setprio 0
	s_setprio 1
	v_mfma_i32_16x16x64_i8 v[128:131], v[160:163], v[182:185], v[128:131]
	v_mfma_i32_16x16x64_i8 v[128:131], v[164:167], v[186:189], v[128:131]
	v_mfma_i32_16x16x64_i8 v[104:107], v[164:167], v[208:211], v[104:107]
	v_mfma_i32_16x16x64_i8 v[104:107], v[160:163], v[204:207], v[104:107]
	v_mfma_i32_16x16x64_i8 v[88:91], v[160:163], v[212:215], v[88:91]
	v_mfma_i32_16x16x64_i8 v[88:91], v[164:167], v[216:219], v[88:91]
	v_mfma_i32_16x16x64_i8 v[72:75], v[164:167], v[224:227], v[72:75]
	v_mfma_i32_16x16x64_i8 v[72:75], v[160:163], v[220:223], v[72:75]
	v_mfma_i32_16x16x64_i8 v[120:123], v[168:171], v[182:185], v[120:123]
	v_mfma_i32_16x16x64_i8 v[120:123], v[178:181], v[186:189], v[120:123]
	v_mfma_i32_16x16x64_i8 v[100:103], v[178:181], v[208:211], v[100:103]
	v_mfma_i32_16x16x64_i8 v[100:103], v[168:171], v[204:207], v[100:103]
	v_mfma_i32_16x16x64_i8 v[84:87], v[168:171], v[212:215], v[84:87]
	v_mfma_i32_16x16x64_i8 v[84:87], v[178:181], v[216:219], v[84:87]
	v_mfma_i32_16x16x64_i8 v[68:71], v[178:181], v[224:227], v[68:71]
	v_mfma_i32_16x16x64_i8 v[68:71], v[168:171], v[220:223], v[68:71]
	s_setprio 0
	s_barrier
	s_add_i32 s50, s50, s43
	v_lshl_add_u64 v[172:173], s[36:37], 0, v[2:3]
	s_mov_b32 m0, s50
	ds_read_b128 v[182:185], v177 offset:16384
	ds_read_b128 v[186:189], v177 offset:17408
	ds_read_b128 v[204:207], v177 offset:18432
	ds_read_b128 v[208:211], v177 offset:19456
	ds_read_b128 v[212:215], v177 offset:20480
	ds_read_b128 v[216:219], v177 offset:21504
	ds_read_b128 v[220:223], v177 offset:22528
	ds_read_b128 v[224:227], v177 offset:23552
	global_load_lds_dwordx4 v[172:173], off
	s_add_i32 m0, s50, 0x2000
	s_add_u32 s50, s36, 0x80000
	v_lshl_add_u64 v[190:191], s[36:37], 0, v[148:149]
	s_addc_u32 s51, s37, 0
	s_add_i32 s56, s56, s43
	global_load_lds_dwordx4 v[190:191], off
	v_lshl_add_u64 v[228:229], s[50:51], 0, v[2:3]
	s_mov_b32 m0, s56
	v_lshl_add_u64 v[240:241], s[40:41], 0, v[150:151]
	global_load_lds_dwordx4 v[228:229], off
	v_lshl_add_u64 v[228:229], s[50:51], 0, v[148:149]
	s_add_i32 m0, s56, 0x2000
	s_nop 0
	global_load_lds_dwordx4 v[228:229], off
	v_lshl_add_u64 v[228:229], s[40:41], 0, v[152:153]
	s_mov_b32 m0, s44
	s_nop 0
	global_load_lds_dwordx4 v[228:229], off
	s_mov_b32 m0, s45
	s_nop 0
	global_load_lds_dwordx4 v[240:241], off
	s_waitcnt vmcnt(8)
	s_waitcnt lgkmcnt(0)
	s_barrier
	s_setprio 1
	s_waitcnt lgkmcnt(0)
	v_mfma_i32_16x16x64_i8 v[64:67], v[116:119], v[182:185], v[64:67]
	v_mfma_i32_16x16x64_i8 v[64:67], v[124:127], v[186:189], v[64:67]
	v_mfma_i32_16x16x64_i8 v[48:51], v[124:127], v[208:211], v[48:51]
	v_mfma_i32_16x16x64_i8 v[48:51], v[116:119], v[204:207], v[48:51]
	v_mfma_i32_16x16x64_i8 v[32:35], v[116:119], v[212:215], v[32:35]
	v_mfma_i32_16x16x64_i8 v[32:35], v[124:127], v[216:219], v[32:35]
	v_mfma_i32_16x16x64_i8 v[16:19], v[124:127], v[224:227], v[16:19]
	v_mfma_i32_16x16x64_i8 v[16:19], v[116:119], v[220:223], v[16:19]
	v_mfma_i32_16x16x64_i8 v[60:63], v[132:135], v[182:185], v[60:63]
	v_mfma_i32_16x16x64_i8 v[60:63], v[136:139], v[186:189], v[60:63]
	v_mfma_i32_16x16x64_i8 v[44:47], v[136:139], v[208:211], v[44:47]
	v_mfma_i32_16x16x64_i8 v[44:47], v[132:135], v[204:207], v[44:47]
	v_mfma_i32_16x16x64_i8 v[28:31], v[132:135], v[212:215], v[28:31]
	v_mfma_i32_16x16x64_i8 v[28:31], v[136:139], v[216:219], v[28:31]
	v_mfma_i32_16x16x64_i8 v[12:15], v[136:139], v[224:227], v[12:15]
	v_mfma_i32_16x16x64_i8 v[12:15], v[132:135], v[220:223], v[12:15]
	s_setprio 0
	s_setprio 1
	v_mfma_i32_16x16x64_i8 v[56:59], v[160:163], v[182:185], v[56:59]
	v_mfma_i32_16x16x64_i8 v[56:59], v[164:167], v[186:189], v[56:59]
	v_mfma_i32_16x16x64_i8 v[40:43], v[164:167], v[208:211], v[40:43]
	v_mfma_i32_16x16x64_i8 v[40:43], v[160:163], v[204:207], v[40:43]
	v_mfma_i32_16x16x64_i8 v[24:27], v[160:163], v[212:215], v[24:27]
	v_mfma_i32_16x16x64_i8 v[24:27], v[164:167], v[216:219], v[24:27]
	v_mfma_i32_16x16x64_i8 v[8:11], v[164:167], v[224:227], v[8:11]
	v_mfma_i32_16x16x64_i8 v[8:11], v[160:163], v[220:223], v[8:11]
	v_mfma_i32_16x16x64_i8 v[52:55], v[168:171], v[182:185], v[52:55]
	v_mfma_i32_16x16x64_i8 v[52:55], v[178:181], v[186:189], v[52:55]
	v_mfma_i32_16x16x64_i8 v[36:39], v[178:181], v[208:211], v[36:39]
	v_mfma_i32_16x16x64_i8 v[36:39], v[168:171], v[204:207], v[36:39]
	v_mfma_i32_16x16x64_i8 v[20:23], v[168:171], v[212:215], v[20:23]
	v_mfma_i32_16x16x64_i8 v[20:23], v[178:181], v[216:219], v[20:23]
	v_mfma_i32_16x16x64_i8 v[4:7], v[178:181], v[224:227], v[4:7]
	v_mfma_i32_16x16x64_i8 v[4:7], v[168:171], v[220:223], v[4:7]
	s_setprio 0
	s_barrier
; #define PG8_STAGE(bufoff, gbase, voff) do { _Pragma("unroll") for (int _i = 0; _i < 2; ++_i) \
;         __builtin_amdgcn_global_load_lds((const unsigned*)((const char*)(gbase) + (voff)[_i]), (PG8_LAS unsigned*)(lds + (bufoff) + ldsw + _i * 8192), 16, 0, 0); } while (0)
; #define PG8_LDA(dst, b, h) do { _Pragma("unroll") for (int m = 0; m < 4; ++m) _Pragma("unroll") for (int k = 0; k < 2; ++k) dst[m][k] = *(const PG8_LAS bf16x8*)(lds + PG8_SA(b, h) + aoff + m * 2048 + k * 1024); } while (0)
; #define PG8_LDB(dst, b, h) do { _Pragma("unroll") for (int n = 0; n < 2; ++n) _Pragma("unroll") for (int k = 0; k < 2; ++k) dst[n][k] = *(const PG8_LAS bf16x8*)(lds + PG8_SB(b, h) + boff + n * 2048 + k * 1024); } while (0)
; #define PG8_WAIT_V(n) asm volatile("s_waitcnt vmcnt(" #n ")" ::: "memory")
; #define PG8_WAIT_L(n) asm volatile("s_waitcnt lgkmcnt(" #n ")" ::: "memory")
; #define PG8_BAR __builtin_amdgcn_s_barrier()
; #define PG8_SCHED __builtin_amdgcn_sched_barrier(0)
; template <class Epi, class Sched, bool ALIGN_EPI = false, bool SP2 = false, bool I8 = false>
; __device__ __forceinline__ void gemm_phase(PG8_LAS unsigned char* lds, const Gemm g, const Sched& S, const Epi& E) {
;     ...
;             PG8_LDB(B0, 1, 0); PG8_LDB(B1, 1, 1); PG8_SCHED; PG8_LDA(At, 1, 0); PG8_STAGE(PG8_SA(0, 1), a2 + hstep, voffA);
;             PG8_WAIT_V(8); PG8_WAIT_L(0); PG8_BAR; PG8_MMA(0, 0, At, B0); PG8_MMA(0, 1, At, B1); PG8_BAR; PG8_SCHED;
;             PG8_LDA(At, 1, 1); PG8_STAGE(PG8_SB(1, 0), b3, voffB); PG8_STAGE(PG8_SB(1, 1), b3 + hstep, voffB); PG8_STAGE(PG8_SA(1, 0), a3, voffA);
;             PG8_WAIT_V(8); PG8_WAIT_L(0); PG8_BAR; PG8_MMA(1, 0, At, B0); PG8_MMA(1, 1, At, B1); PG8_BAR; PG8_SCHED;
	s_add_i32 s50, 0, 0x18000
	s_add_i32 s51, 0, 0x1c000
	v_add_u32_e32 v136, s50, v175
	v_add_u32_e32 v178, s51, v175
	ds_read_b128 v[116:119], v136
	ds_read_b128 v[124:127], v136 offset:1024
	ds_read_b128 v[132:135], v136 offset:2048
	ds_read_b128 v[136:139], v136 offset:3072
	ds_read_b128 v[160:163], v178
	ds_read_b128 v[164:167], v178 offset:1024
	ds_read_b128 v[168:171], v178 offset:2048
	ds_read_b128 v[178:181], v178 offset:3072
	s_add_u32 s40, s40, 0x80000
	s_addc_u32 s41, s41, 0
	s_mov_b32 m0, s46
	v_lshl_add_u64 v[242:243], s[40:41], 0, v[152:153]
	ds_read_b128 v[182:185], v177 offset:32768
	ds_read_b128 v[186:189], v177 offset:33792
	ds_read_b128 v[204:207], v177 offset:34816
	ds_read_b128 v[208:211], v177 offset:35840
	ds_read_b128 v[212:215], v177 offset:36864
	ds_read_b128 v[216:219], v177 offset:37888
	ds_read_b128 v[220:223], v177 offset:38912
	ds_read_b128 v[224:227], v177 offset:39936
	global_load_lds_dwordx4 v[242:243], off
	v_lshl_add_u64 v[242:243], s[40:41], 0, v[150:151]
	s_mov_b32 m0, s47
	s_nop 0
	global_load_lds_dwordx4 v[242:243], off
	s_waitcnt vmcnt(8)
	s_waitcnt lgkmcnt(0)
	s_barrier
	s_setprio 1
	s_waitcnt lgkmcnt(0)
	v_mfma_i32_16x16x64_i8 v[144:147], v[116:119], v[182:185], v[144:147]
	v_mfma_i32_16x16x64_i8 v[144:147], v[124:127], v[186:189], v[144:147]
	v_mfma_i32_16x16x64_i8 v[112:115], v[124:127], v[208:211], v[112:115]
	v_mfma_i32_16x16x64_i8 v[112:115], v[116:119], v[204:207], v[112:115]
	v_mfma_i32_16x16x64_i8 v[96:99], v[116:119], v[212:215], v[96:99]
	v_mfma_i32_16x16x64_i8 v[96:99], v[124:127], v[216:219], v[96:99]
	v_mfma_i32_16x16x64_i8 v[80:83], v[124:127], v[224:227], v[80:83]
	v_mfma_i32_16x16x64_i8 v[80:83], v[116:119], v[220:223], v[80:83]
	v_mfma_i32_16x16x64_i8 v[140:143], v[132:135], v[182:185], v[140:143]
	v_mfma_i32_16x16x64_i8 v[140:143], v[136:139], v[186:189], v[140:143]
	v_mfma_i32_16x16x64_i8 v[108:111], v[136:139], v[208:211], v[108:111]
	v_mfma_i32_16x16x64_i8 v[108:111], v[132:135], v[204:207], v[108:111]
	v_mfma_i32_16x16x64_i8 v[92:95], v[132:135], v[212:215], v[92:95]
	v_mfma_i32_16x16x64_i8 v[92:95], v[136:139], v[216:219], v[92:95]
	v_mfma_i32_16x16x64_i8 v[76:79], v[136:139], v[224:227], v[76:79]
	v_mfma_i32_16x16x64_i8 v[76:79], v[132:135], v[220:223], v[76:79]
	s_setprio 0
	s_setprio 1
	v_mfma_i32_16x16x64_i8 v[128:131], v[160:163], v[182:185], v[128:131]
	v_mfma_i32_16x16x64_i8 v[128:131], v[164:167], v[186:189], v[128:131]
	v_mfma_i32_16x16x64_i8 v[104:107], v[164:167], v[208:211], v[104:107]
	v_mfma_i32_16x16x64_i8 v[104:107], v[160:163], v[204:207], v[104:107]
	v_mfma_i32_16x16x64_i8 v[88:91], v[160:163], v[212:215], v[88:91]
	v_mfma_i32_16x16x64_i8 v[88:91], v[164:167], v[216:219], v[88:91]
	v_mfma_i32_16x16x64_i8 v[72:75], v[164:167], v[224:227], v[72:75]
	v_mfma_i32_16x16x64_i8 v[72:75], v[160:163], v[220:223], v[72:75]
	v_mfma_i32_16x16x64_i8 v[120:123], v[168:171], v[182:185], v[120:123]
	v_mfma_i32_16x16x64_i8 v[120:123], v[178:181], v[186:189], v[120:123]
	v_mfma_i32_16x16x64_i8 v[100:103], v[178:181], v[208:211], v[100:103]
	v_mfma_i32_16x16x64_i8 v[100:103], v[168:171], v[204:207], v[100:103]
	v_mfma_i32_16x16x64_i8 v[84:87], v[168:171], v[212:215], v[84:87]
	v_mfma_i32_16x16x64_i8 v[84:87], v[178:181], v[216:219], v[84:87]
	v_mfma_i32_16x16x64_i8 v[68:71], v[178:181], v[224:227], v[68:71]
	v_mfma_i32_16x16x64_i8 v[68:71], v[168:171], v[220:223], v[68:71]
	s_setprio 0
	s_barrier
	s_add_i32 s40, s50, s43
	v_lshl_add_u64 v[172:173], v[172:173], 0, s[84:85]
	s_mov_b32 m0, s40
	ds_read_b128 v[182:185], v177 offset:49152
	ds_read_b128 v[186:189], v177 offset:50176
	ds_read_b128 v[204:207], v177 offset:51200
	ds_read_b128 v[208:211], v177 offset:52224
	ds_read_b128 v[212:215], v177 offset:53248
	ds_read_b128 v[216:219], v177 offset:54272
	ds_read_b128 v[220:223], v177 offset:55296
	ds_read_b128 v[224:227], v177 offset:56320
	global_load_lds_dwordx4 v[172:173], off
	s_add_i32 m0, s40, 0x2000
	s_add_u32 s36, s36, 0x80080
	v_lshl_add_u64 v[172:173], v[190:191], 0, s[84:85]
	s_addc_u32 s37, s37, 0
	s_add_i32 s40, s51, s43
	global_load_lds_dwordx4 v[172:173], off
	v_lshl_add_u64 v[172:173], s[36:37], 0, v[2:3]
	s_mov_b32 m0, s40
	s_nop 0
	global_load_lds_dwordx4 v[172:173], off
	v_lshl_add_u64 v[172:173], s[36:37], 0, v[148:149]
	s_add_i32 m0, s40, 0x2000
	s_nop 0
	global_load_lds_dwordx4 v[172:173], off
	v_lshl_add_u64 v[172:173], v[228:229], 0, s[84:85]
	s_mov_b32 m0, s52
	s_nop 0
	global_load_lds_dwordx4 v[172:173], off
	v_lshl_add_u64 v[172:173], v[240:241], 0, s[84:85]
	s_mov_b32 m0, s53
	s_nop 0
	global_load_lds_dwordx4 v[172:173], off
	s_waitcnt vmcnt(8)
	s_waitcnt lgkmcnt(0)
	s_barrier
	s_setprio 1
	s_waitcnt lgkmcnt(0)
	v_mfma_i32_16x16x64_i8 v[64:67], v[116:119], v[182:185], v[64:67]
	v_mfma_i32_16x16x64_i8 v[64:67], v[124:127], v[186:189], v[64:67]
	v_mfma_i32_16x16x64_i8 v[48:51], v[124:127], v[208:211], v[48:51]
	v_mfma_i32_16x16x64_i8 v[48:51], v[116:119], v[204:207], v[48:51]
	v_mfma_i32_16x16x64_i8 v[32:35], v[116:119], v[212:215], v[32:35]
	v_mfma_i32_16x16x64_i8 v[32:35], v[124:127], v[216:219], v[32:35]
	v_mfma_i32_16x16x64_i8 v[16:19], v[124:127], v[224:227], v[16:19]
	v_mfma_i32_16x16x64_i8 v[16:19], v[116:119], v[220:223], v[16:19]
	v_mfma_i32_16x16x64_i8 v[60:63], v[132:135], v[182:185], v[60:63]
	v_mfma_i32_16x16x64_i8 v[60:63], v[136:139], v[186:189], v[60:63]
	v_mfma_i32_16x16x64_i8 v[44:47], v[136:139], v[208:211], v[44:47]
	v_mfma_i32_16x16x64_i8 v[44:47], v[132:135], v[204:207], v[44:47]
	v_mfma_i32_16x16x64_i8 v[28:31], v[132:135], v[212:215], v[28:31]
	v_mfma_i32_16x16x64_i8 v[28:31], v[136:139], v[216:219], v[28:31]
	v_mfma_i32_16x16x64_i8 v[12:15], v[136:139], v[224:227], v[12:15]
	v_mfma_i32_16x16x64_i8 v[12:15], v[132:135], v[220:223], v[12:15]
	s_setprio 0
	s_setprio 1
	v_mfma_i32_16x16x64_i8 v[56:59], v[160:163], v[182:185], v[56:59]
	v_mfma_i32_16x16x64_i8 v[56:59], v[164:167], v[186:189], v[56:59]
	v_mfma_i32_16x16x64_i8 v[40:43], v[164:167], v[208:211], v[40:43]
	v_mfma_i32_16x16x64_i8 v[40:43], v[160:163], v[204:207], v[40:43]
	v_mfma_i32_16x16x64_i8 v[24:27], v[160:163], v[212:215], v[24:27]
	v_mfma_i32_16x16x64_i8 v[24:27], v[164:167], v[216:219], v[24:27]
	v_mfma_i32_16x16x64_i8 v[8:11], v[164:167], v[224:227], v[8:11]
	v_mfma_i32_16x16x64_i8 v[8:11], v[160:163], v[220:223], v[8:11]
	v_mfma_i32_16x16x64_i8 v[52:55], v[168:171], v[182:185], v[52:55]
	v_mfma_i32_16x16x64_i8 v[52:55], v[178:181], v[186:189], v[52:55]
	v_mfma_i32_16x16x64_i8 v[36:39], v[178:181], v[208:211], v[36:39]
	v_mfma_i32_16x16x64_i8 v[36:39], v[168:171], v[204:207], v[36:39]
	v_mfma_i32_16x16x64_i8 v[20:23], v[168:171], v[212:215], v[20:23]
	v_mfma_i32_16x16x64_i8 v[20:23], v[178:181], v[216:219], v[20:23]
	v_mfma_i32_16x16x64_i8 v[4:7], v[178:181], v[224:227], v[4:7]
	v_mfma_i32_16x16x64_i8 v[4:7], v[168:171], v[220:223], v[4:7]
	s_setprio 0
	s_barrier
	s_add_i32 s76, s76, 2
	s_add_u32 s26, s26, 0x100
	s_addc_u32 s27, s27, 0
	s_add_u32 s72, s72, 0x100
	s_addc_u32 s73, s73, 0
	s_cmp_gt_u32 s76, 29
	s_cbranch_scc0 .LBB0_208

; #define PG8_STAGE(bufoff, gbase, voff) do { _Pragma("unroll") for (int _i = 0; _i < 2; ++_i) \
;         __builtin_amdgcn_global_load_lds((const unsigned*)((const char*)(gbase) + (voff)[_i]), (PG8_LAS unsigned*)(lds + (bufoff) + ldsw + _i * 8192), 16, 0, 0); } while (0)
; #define PG8_LDA(dst, b, h) do { _Pragma("unroll") for (int m = 0; m < 4; ++m) _Pragma("unroll") for (int k = 0; k < 2; ++k) dst[m][k] = *(const PG8_LAS bf16x8*)(lds + PG8_SA(b, h) + aoff + m * 2048 + k * 1024); } while (0)
; #define PG8_LDB(dst, b, h) do { _Pragma("unroll") for (int n = 0; n < 2; ++n) _Pragma("unroll") for (int k = 0; k < 2; ++k) dst[n][k] = *(const PG8_LAS bf16x8*)(lds + PG8_SB(b, h) + boff + n * 2048 + k * 1024); } while (0)
; #define PG8_WAIT_V(n) asm volatile("s_waitcnt vmcnt(" #n ")" ::: "memory")
; #define PG8_WAIT_L(n) asm volatile("s_waitcnt lgkmcnt(" #n ")" ::: "memory")
; #define PG8_BAR __builtin_amdgcn_s_barrier()
; #define PG8_SCHED __builtin_amdgcn_sched_barrier(0)
; template <class Epi, class Sched, bool ALIGN_EPI = false, bool SP2 = false, bool I8 = false>
; __device__ __forceinline__ void gemm_phase(PG8_LAS unsigned char* lds, const Gemm g, const Sched& S, const Epi& E) {
;     ...
;         const bool has_next = S.next(ui + 1, nxt);
;         const char* nA = has_next ? (const char*)g.A + (size_t)nxt.pm * tstep : cA; const char* nB = has_next ? (const char*)g.Bt + (size_t)nxt.pn * tstep : cB;
;         for (int t = 0; t < nt; t += 2) {
;             const bool last = (t == nt - 2);
;             const char* a1 = cA + (size_t)(t + 1) * kstep;
;             const char* a2 = last ? nA : cA + (size_t)(t + 2) * kstep; const char* b2 = last ? nB : cB + (size_t)(t + 2) * kstep;
;             const char* a3 = a2 + kstep; const char* b3 = b2 + kstep;
;             if (last && has_next) S.a_ready(nxt);
;             if constexpr (SP2) {
;             PG8_LDB(B0, 0, 0); PG8_LDB(B1, 0, 1); PG8_SCHED; PG8_LDA(At, 0, 0); PG8_STAGE(PG8_SA(1, 1), a1 + hstep, voffA);
;             PG8_WAIT_V(8); PG8_WAIT_L(0); PG8_BAR; PG8_MMA(0, 0, At, B0); PG8_MMA(0, 1, At, B1); PG8_BAR; PG8_SCHED;
;             PG8_LDA(At, 0, 1); PG8_STAGE(PG8_SB(0, 0), b2, voffB); PG8_STAGE(PG8_SB(0, 1), b2 + hstep, voffB); PG8_STAGE(PG8_SA(0, 0), a2, voffA);
.LBB0_1590:
	s_ashr_i32 s25, s24, 31
	s_lshl_b64 s[26:27], s[24:25], 20
	s_add_u32 s26, s28, s26
	s_addc_u32 s27, s42, s27
	s_and_b64 s[36:37], s[10:11], exec
	s_cselect_b32 s25, s27, s41
	s_cselect_b32 s57, s26, s40
	s_ashr_i32 s23, s22, 31
	s_lshl_b64 s[36:37], s[22:23], 20
	s_add_u32 s36, s43, s36
	s_addc_u32 s37, s46, s37
	s_and_b64 s[48:49], s[10:11], exec
	s_cselect_b32 s23, s37, s45
	s_cselect_b32 s58, s36, s44
	s_add_u32 s40, s40, 0x80080
	s_addc_u32 s41, s41, 0
	s_add_u32 s59, s44, 0x100
	s_addc_u32 s60, s45, 0
	s_mov_b32 s61, -2
	s_add_u32 s44, s40, 0xfff80080
	s_addc_u32 s45, s41, -1
	s_add_i32 s64, 0, 0x10000
	s_cmp_eq_u32 s61, 28
	s_cselect_b32 s49, s25, s45
	s_cselect_b32 s48, s57, s44
	s_cselect_b32 s45, s23, s60
	s_cselect_b32 s44, s58, s59
	s_add_i32 s67, 0, 0x14000
	v_add_u32_e32 v144, s64, v167
	v_add_u32_e32 v158, s67, v167
	ds_read_b128 v[36:39], v144
	ds_read_b128 v[44:47], v144 offset:1024
	ds_read_b128 v[140:143], v144 offset:2048
	ds_read_b128 v[144:147], v144 offset:3072
	ds_read_b128 v[160:163], v158
	ds_read_b128 v[172:175], v158 offset:1024
	ds_read_b128 v[176:179], v158 offset:2048
	ds_read_b128 v[180:183], v158 offset:3072
	v_lshl_add_u64 v[164:165], s[40:41], 0, v[154:155]
	s_add_i32 m0, s50, 0xc000
	ds_read_b128 v[184:187], v171
	ds_read_b128 v[188:191], v171 offset:1024
	ds_read_b128 v[204:207], v171 offset:2048
	ds_read_b128 v[208:211], v171 offset:3072
	ds_read_b128 v[212:215], v171 offset:4096
	ds_read_b128 v[216:219], v171 offset:5120
	ds_read_b128 v[220:223], v171 offset:6144
	ds_read_b128 v[224:227], v171 offset:7168
	global_load_lds_dwordx4 v[164:165], off
	v_lshl_add_u64 v[164:165], s[40:41], 0, v[156:157]
	s_add_i32 m0, s50, 0xe000
	s_nop 0
	global_load_lds_dwordx4 v[164:165], off
	s_waitcnt vmcnt(8)
	s_waitcnt lgkmcnt(0)
	s_barrier
	s_setprio 1
	s_waitcnt lgkmcnt(0)
	v_mfma_i32_16x16x64_i8 v[136:139], v[36:39], v[184:187], 0
	v_mfma_i32_16x16x64_i8 v[136:139], v[44:47], v[188:191], v[136:139]
	v_mfma_i32_16x16x64_i8 v[120:123], v[44:47], v[208:211], 0
	v_mfma_i32_16x16x64_i8 v[120:123], v[36:39], v[204:207], v[120:123]
	v_mfma_i32_16x16x64_i8 v[104:107], v[36:39], v[212:215], 0
	v_mfma_i32_16x16x64_i8 v[104:107], v[44:47], v[216:219], v[104:107]
	v_mfma_i32_16x16x64_i8 v[88:91], v[44:47], v[224:227], 0
	v_mfma_i32_16x16x64_i8 v[88:91], v[36:39], v[220:223], v[88:91]
	v_mfma_i32_16x16x64_i8 v[128:131], v[140:143], v[184:187], 0
	v_mfma_i32_16x16x64_i8 v[128:131], v[144:147], v[188:191], v[128:131]
	v_mfma_i32_16x16x64_i8 v[112:115], v[144:147], v[208:211], 0
	v_mfma_i32_16x16x64_i8 v[112:115], v[140:143], v[204:207], v[112:115]
	v_mfma_i32_16x16x64_i8 v[96:99], v[140:143], v[212:215], 0
	v_mfma_i32_16x16x64_i8 v[96:99], v[144:147], v[216:219], v[96:99]
	v_mfma_i32_16x16x64_i8 v[80:83], v[144:147], v[224:227], 0
	v_mfma_i32_16x16x64_i8 v[80:83], v[140:143], v[220:223], v[80:83]
	s_setprio 0
	s_setprio 1
	v_mfma_i32_16x16x64_i8 v[132:135], v[160:163], v[184:187], 0
	v_mfma_i32_16x16x64_i8 v[132:135], v[172:175], v[188:191], v[132:135]
	v_mfma_i32_16x16x64_i8 v[116:119], v[172:175], v[208:211], 0
	v_mfma_i32_16x16x64_i8 v[116:119], v[160:163], v[204:207], v[116:119]
	v_mfma_i32_16x16x64_i8 v[100:103], v[160:163], v[212:215], 0
	v_mfma_i32_16x16x64_i8 v[100:103], v[172:175], v[216:219], v[100:103]
	v_mfma_i32_16x16x64_i8 v[84:87], v[172:175], v[224:227], 0
	v_mfma_i32_16x16x64_i8 v[84:87], v[160:163], v[220:223], v[84:87]
	v_mfma_i32_16x16x64_i8 v[124:127], v[176:179], v[184:187], 0
	v_mfma_i32_16x16x64_i8 v[124:127], v[180:183], v[188:191], v[124:127]
	v_mfma_i32_16x16x64_i8 v[108:111], v[180:183], v[208:211], 0
	v_mfma_i32_16x16x64_i8 v[108:111], v[176:179], v[204:207], v[108:111]
	v_mfma_i32_16x16x64_i8 v[92:95], v[176:179], v[212:215], 0
	v_mfma_i32_16x16x64_i8 v[92:95], v[180:183], v[216:219], v[92:95]
	v_mfma_i32_16x16x64_i8 v[76:79], v[180:183], v[224:227], 0
	v_mfma_i32_16x16x64_i8 v[76:79], v[176:179], v[220:223], v[76:79]
	s_setprio 0
	s_barrier
	s_add_i32 s64, s64, s47
	v_lshl_add_u64 v[164:165], s[44:45], 0, v[2:3]
	s_mov_b32 m0, s64
	ds_read_b128 v[184:187], v171 offset:16384
	ds_read_b128 v[188:191], v171 offset:17408
	ds_read_b128 v[204:207], v171 offset:18432
	ds_read_b128 v[208:211], v171 offset:19456
	ds_read_b128 v[212:215], v171 offset:20480
	ds_read_b128 v[216:219], v171 offset:21504
	ds_read_b128 v[220:223], v171 offset:22528
	ds_read_b128 v[224:227], v171 offset:23552
	global_load_lds_dwordx4 v[164:165], off
	s_add_i32 m0, s64, 0x2000
	s_add_u32 s64, s44, 0x80000
	v_lshl_add_u64 v[228:229], s[44:45], 0, v[148:149]
	s_addc_u32 s65, s45, 0
	s_add_i32 s67, s67, s47
	global_load_lds_dwordx4 v[228:229], off
	v_lshl_add_u64 v[240:241], s[64:65], 0, v[2:3]
	s_mov_b32 m0, s67
	v_lshl_add_u64 v[242:243], s[48:49], 0, v[150:151]
	global_load_lds_dwordx4 v[240:241], off
	v_lshl_add_u64 v[240:241], s[64:65], 0, v[148:149]
	s_add_i32 m0, s67, 0x2000
	s_nop 0
	global_load_lds_dwordx4 v[240:241], off
	v_lshl_add_u64 v[240:241], s[48:49], 0, v[152:153]
	s_mov_b32 m0, s50
	s_nop 0
	global_load_lds_dwordx4 v[240:241], off
	s_mov_b32 m0, s51
	s_nop 0
	global_load_lds_dwordx4 v[242:243], off
	s_waitcnt vmcnt(8)
	s_waitcnt lgkmcnt(0)
	s_barrier
; #define PG8_STAGE(bufoff, gbase, voff) do { _Pragma("unroll") for (int _i = 0; _i < 2; ++_i) \
;         __builtin_amdgcn_global_load_lds((const unsigned*)((const char*)(gbase) + (voff)[_i]), (PG8_LAS unsigned*)(lds + (bufoff) + ldsw + _i * 8192), 16, 0, 0); } while (0)
; #define PG8_LDA(dst, b, h) do { _Pragma("unroll") for (int m = 0; m < 4; ++m) _Pragma("unroll") for (int k = 0; k < 2; ++k) dst[m][k] = *(const PG8_LAS bf16x8*)(lds + PG8_SA(b, h) + aoff + m * 2048 + k * 1024); } while (0)
; #define PG8_LDB(dst, b, h) do { _Pragma("unroll") for (int n = 0; n < 2; ++n) _Pragma("unroll") for (int k = 0; k < 2; ++k) dst[n][k] = *(const PG8_LAS bf16x8*)(lds + PG8_SB(b, h) + boff + n * 2048 + k * 1024); } while (0)
; #define PG8_WAIT_V(n) asm volatile("s_waitcnt vmcnt(" #n ")" ::: "memory")
; #define PG8_WAIT_L(n) asm volatile("s_waitcnt lgkmcnt(" #n ")" ::: "memory")
; #define PG8_BAR __builtin_amdgcn_s_barrier()
; #define PG8_SCHED __builtin_amdgcn_sched_barrier(0)
; template <class Epi, class Sched, bool ALIGN_EPI = false, bool SP2 = false, bool I8 = false>
; __device__ __forceinline__ void gemm_phase(PG8_LAS unsigned char* lds, const Gemm g, const Sched& S, const Epi& E) {
;     ...
;             PG8_WAIT_V(8); PG8_WAIT_L(0); PG8_BAR; PG8_MMA(1, 0, At, B0); PG8_MMA(1, 1, At, B1); PG8_BAR; PG8_SCHED;
;             PG8_LDB(B0, 1, 0); PG8_LDB(B1, 1, 1); PG8_SCHED; PG8_LDA(At, 1, 0); PG8_STAGE(PG8_SA(0, 1), a2 + hstep, voffA);
;             PG8_WAIT_V(8); PG8_WAIT_L(0); PG8_BAR; PG8_MMA(0, 0, At, B0); PG8_MMA(0, 1, At, B1); PG8_BAR; PG8_SCHED;
	s_setprio 1
	s_waitcnt lgkmcnt(0)
	v_mfma_i32_16x16x64_i8 v[72:75], v[36:39], v[184:187], 0
	v_mfma_i32_16x16x64_i8 v[72:75], v[44:47], v[188:191], v[72:75]
	v_mfma_i32_16x16x64_i8 v[56:59], v[44:47], v[208:211], 0
	v_mfma_i32_16x16x64_i8 v[56:59], v[36:39], v[204:207], v[56:59]
	v_mfma_i32_16x16x64_i8 v[32:35], v[36:39], v[212:215], 0
	v_mfma_i32_16x16x64_i8 v[32:35], v[44:47], v[216:219], v[32:35]
	v_mfma_i32_16x16x64_i8 v[16:19], v[44:47], v[224:227], 0
	v_mfma_i32_16x16x64_i8 v[16:19], v[36:39], v[220:223], v[16:19]
	v_mfma_i32_16x16x64_i8 v[64:67], v[140:143], v[184:187], 0
	v_mfma_i32_16x16x64_i8 v[64:67], v[144:147], v[188:191], v[64:67]
	v_mfma_i32_16x16x64_i8 v[48:51], v[144:147], v[208:211], 0
	v_mfma_i32_16x16x64_i8 v[48:51], v[140:143], v[204:207], v[48:51]
	v_mfma_i32_16x16x64_i8 v[24:27], v[140:143], v[212:215], 0
	v_mfma_i32_16x16x64_i8 v[24:27], v[144:147], v[216:219], v[24:27]
	v_mfma_i32_16x16x64_i8 v[8:11], v[144:147], v[224:227], 0
	v_mfma_i32_16x16x64_i8 v[8:11], v[140:143], v[220:223], v[8:11]
	s_setprio 0
	s_setprio 1
	v_mfma_i32_16x16x64_i8 v[52:55], v[160:163], v[204:207], 0
	v_mfma_i32_16x16x64_i8 v[52:55], v[172:175], v[208:211], v[52:55]
	v_mfma_i32_16x16x64_i8 v[28:31], v[172:175], v[216:219], 0
	v_mfma_i32_16x16x64_i8 v[28:31], v[160:163], v[212:215], v[28:31]
	v_mfma_i32_16x16x64_i8 v[12:15], v[160:163], v[220:223], 0
	v_mfma_i32_16x16x64_i8 v[12:15], v[172:175], v[224:227], v[12:15]
	v_mfma_i32_16x16x64_i8 v[36:39], v[172:175], v[188:191], 0
	v_mfma_i32_16x16x64_i8 v[36:39], v[160:163], v[184:187], v[36:39]
	v_mfma_i32_16x16x64_i8 v[40:43], v[176:179], v[204:207], 0
	v_mfma_i32_16x16x64_i8 v[40:43], v[180:183], v[208:211], v[40:43]
	v_mfma_i32_16x16x64_i8 v[20:23], v[180:183], v[216:219], 0
	v_mfma_i32_16x16x64_i8 v[20:23], v[176:179], v[212:215], v[20:23]
	v_mfma_i32_16x16x64_i8 v[4:7], v[176:179], v[220:223], 0
	v_mfma_i32_16x16x64_i8 v[4:7], v[180:183], v[224:227], v[4:7]
	v_mfma_i32_16x16x64_i8 v[44:47], v[180:183], v[188:191], 0
	v_mfma_i32_16x16x64_i8 v[44:47], v[176:179], v[184:187], v[44:47]
	s_setprio 0
	s_barrier
	s_add_i32 s64, 0, 0x18000
	s_add_i32 s65, 0, 0x1c000
	v_add_u32_e32 v144, s64, v167
	v_add_u32_e32 v158, s65, v167
	ds_read_b128 v[60:63], v144
	ds_read_b128 v[68:71], v144 offset:1024
	ds_read_b128 v[140:143], v144 offset:2048
	ds_read_b128 v[144:147], v144 offset:3072
	ds_read_b128 v[160:163], v158
	ds_read_b128 v[172:175], v158 offset:1024
	ds_read_b128 v[176:179], v158 offset:2048
	ds_read_b128 v[180:183], v158 offset:3072
	s_add_u32 s48, s48, 0x80000
	s_addc_u32 s49, s49, 0
	s_mov_b32 m0, s52
	v_lshl_add_u64 v[244:245], s[48:49], 0, v[152:153]
	ds_read_b128 v[184:187], v171 offset:32768
	ds_read_b128 v[188:191], v171 offset:33792
	ds_read_b128 v[204:207], v171 offset:34816
	ds_read_b128 v[208:211], v171 offset:35840
	ds_read_b128 v[212:215], v171 offset:36864
	ds_read_b128 v[216:219], v171 offset:37888
	ds_read_b128 v[220:223], v171 offset:38912
	ds_read_b128 v[224:227], v171 offset:39936
	global_load_lds_dwordx4 v[244:245], off
	v_lshl_add_u64 v[244:245], s[48:49], 0, v[150:151]
	s_mov_b32 m0, s53
	s_nop 0
	global_load_lds_dwordx4 v[244:245], off
	s_waitcnt vmcnt(8)
	s_waitcnt lgkmcnt(0)
	s_barrier
	s_setprio 1
	s_waitcnt lgkmcnt(0)
	v_mfma_i32_16x16x64_i8 v[136:139], v[60:63], v[184:187], v[136:139]
	v_mfma_i32_16x16x64_i8 v[136:139], v[68:71], v[188:191], v[136:139]
	v_mfma_i32_16x16x64_i8 v[120:123], v[68:71], v[208:211], v[120:123]
	v_mfma_i32_16x16x64_i8 v[120:123], v[60:63], v[204:207], v[120:123]
	v_mfma_i32_16x16x64_i8 v[104:107], v[60:63], v[212:215], v[104:107]
	v_mfma_i32_16x16x64_i8 v[104:107], v[68:71], v[216:219], v[104:107]
	v_mfma_i32_16x16x64_i8 v[88:91], v[68:71], v[224:227], v[88:91]
	v_mfma_i32_16x16x64_i8 v[88:91], v[60:63], v[220:223], v[88:91]
	v_mfma_i32_16x16x64_i8 v[128:131], v[140:143], v[184:187], v[128:131]
	v_mfma_i32_16x16x64_i8 v[128:131], v[144:147], v[188:191], v[128:131]
	v_mfma_i32_16x16x64_i8 v[112:115], v[144:147], v[208:211], v[112:115]
	v_mfma_i32_16x16x64_i8 v[112:115], v[140:143], v[204:207], v[112:115]
	v_mfma_i32_16x16x64_i8 v[96:99], v[140:143], v[212:215], v[96:99]
	v_mfma_i32_16x16x64_i8 v[96:99], v[144:147], v[216:219], v[96:99]
	v_mfma_i32_16x16x64_i8 v[80:83], v[144:147], v[224:227], v[80:83]
	v_mfma_i32_16x16x64_i8 v[80:83], v[140:143], v[220:223], v[80:83]
	s_setprio 0
	s_setprio 1
	v_mfma_i32_16x16x64_i8 v[132:135], v[160:163], v[184:187], v[132:135]
	v_mfma_i32_16x16x64_i8 v[132:135], v[172:175], v[188:191], v[132:135]
	v_mfma_i32_16x16x64_i8 v[116:119], v[172:175], v[208:211], v[116:119]
	v_mfma_i32_16x16x64_i8 v[116:119], v[160:163], v[204:207], v[116:119]
	v_mfma_i32_16x16x64_i8 v[100:103], v[160:163], v[212:215], v[100:103]
	v_mfma_i32_16x16x64_i8 v[100:103], v[172:175], v[216:219], v[100:103]
	v_mfma_i32_16x16x64_i8 v[84:87], v[172:175], v[224:227], v[84:87]
	v_mfma_i32_16x16x64_i8 v[84:87], v[160:163], v[220:223], v[84:87]
	v_mfma_i32_16x16x64_i8 v[124:127], v[176:179], v[184:187], v[124:127]
	v_mfma_i32_16x16x64_i8 v[124:127], v[180:183], v[188:191], v[124:127]
	v_mfma_i32_16x16x64_i8 v[108:111], v[180:183], v[208:211], v[108:111]
	v_mfma_i32_16x16x64_i8 v[108:111], v[176:179], v[204:207], v[108:111]
	v_mfma_i32_16x16x64_i8 v[92:95], v[176:179], v[212:215], v[92:95]
	v_mfma_i32_16x16x64_i8 v[92:95], v[180:183], v[216:219], v[92:95]
	v_mfma_i32_16x16x64_i8 v[76:79], v[180:183], v[224:227], v[76:79]
	v_mfma_i32_16x16x64_i8 v[76:79], v[176:179], v[220:223], v[76:79]
	s_setprio 0
	s_barrier
; #define PG8_STAGE(bufoff, gbase, voff) do { _Pragma("unroll") for (int _i = 0; _i < 2; ++_i) \
;         __builtin_amdgcn_global_load_lds((const unsigned*)((const char*)(gbase) + (voff)[_i]), (PG8_LAS unsigned*)(lds + (bufoff) + ldsw + _i * 8192), 16, 0, 0); } while (0)
; #define PG8_LDA(dst, b, h) do { _Pragma("unroll") for (int m = 0; m < 4; ++m) _Pragma("unroll") for (int k = 0; k < 2; ++k) dst[m][k] = *(const PG8_LAS bf16x8*)(lds + PG8_SA(b, h) + aoff + m * 2048 + k * 1024); } while (0)
; #define PG8_WAIT_V(n) asm volatile("s_waitcnt vmcnt(" #n ")" ::: "memory")
; #define PG8_WAIT_L(n) asm volatile("s_waitcnt lgkmcnt(" #n ")" ::: "memory")
; #define PG8_BAR __builtin_amdgcn_s_barrier()
; template <class Epi, class Sched, bool ALIGN_EPI = false, bool SP2 = false, bool I8 = false>
; __device__ __forceinline__ void gemm_phase(PG8_LAS unsigned char* lds, const Gemm g, const Sched& S, const Epi& E) {
;     ...
;         for (int t = 0; t < nt; t += 2) {
;             const bool last = (t == nt - 2);
;             const char* a1 = cA + (size_t)(t + 1) * kstep;
;             const char* a2 = last ? nA : cA + (size_t)(t + 2) * kstep; const char* b2 = last ? nB : cB + (size_t)(t + 2) * kstep;
;             const char* a3 = a2 + kstep; const char* b3 = b2 + kstep;
;             if (last && has_next) S.a_ready(nxt);
;             if constexpr (SP2) {
;             PG8_LDB(B0, 0, 0); PG8_LDB(B1, 0, 1); PG8_SCHED; PG8_LDA(At, 0, 0); PG8_STAGE(PG8_SA(1, 1), a1 + hstep, voffA);
;             PG8_WAIT_V(8); PG8_WAIT_L(0); PG8_BAR; PG8_MMA(0, 0, At, B0); PG8_MMA(0, 1, At, B1); PG8_BAR; PG8_SCHED;
;             PG8_LDA(At, 0, 1); PG8_STAGE(PG8_SB(0, 0), b2, voffB); PG8_STAGE(PG8_SB(0, 1), b2 + hstep, voffB); PG8_STAGE(PG8_SA(0, 0), a2, voffA);
;             PG8_WAIT_V(8); PG8_WAIT_L(0); PG8_BAR; PG8_MMA(1, 0, At, B0); PG8_MMA(1, 1, At, B1); PG8_BAR; PG8_SCHED;
;             PG8_LDB(B0, 1, 0); PG8_LDB(B1, 1, 1); PG8_SCHED; PG8_LDA(At, 1, 0); PG8_STAGE(PG8_SA(0, 1), a2 + hstep, voffA);
;             PG8_WAIT_V(8); PG8_WAIT_L(0); PG8_BAR; PG8_MMA(0, 0, At, B0); PG8_MMA(0, 1, At, B1); PG8_BAR; PG8_SCHED;
;             PG8_LDA(At, 1, 1); PG8_STAGE(PG8_SB(1, 0), b3, voffB); PG8_STAGE(PG8_SB(1, 1), b3 + hstep, voffB); PG8_STAGE(PG8_SA(1, 0), a3, voffA);
;             PG8_WAIT_V(8); PG8_WAIT_L(0); PG8_BAR; PG8_MMA(1, 0, At, B0); PG8_MMA(1, 1, At, B1); PG8_BAR; PG8_SCHED;
	s_add_i32 s48, s64, s47
	v_lshl_add_u64 v[164:165], v[164:165], 0, s[84:85]
	s_mov_b32 m0, s48
	ds_read_b128 v[184:187], v171 offset:49152
	ds_read_b128 v[188:191], v171 offset:50176
	ds_read_b128 v[204:207], v171 offset:51200
	ds_read_b128 v[208:211], v171 offset:52224
	ds_read_b128 v[212:215], v171 offset:53248
	ds_read_b128 v[216:219], v171 offset:54272
	ds_read_b128 v[220:223], v171 offset:55296
	ds_read_b128 v[224:227], v171 offset:56320
	global_load_lds_dwordx4 v[164:165], off
	s_add_i32 m0, s48, 0x2000
	s_add_u32 s44, s44, 0x80080
	v_lshl_add_u64 v[164:165], v[228:229], 0, s[84:85]
	s_addc_u32 s45, s45, 0
	s_add_i32 s48, s65, s47
	global_load_lds_dwordx4 v[164:165], off
	v_lshl_add_u64 v[164:165], s[44:45], 0, v[2:3]
	s_mov_b32 m0, s48
	s_nop 0
	global_load_lds_dwordx4 v[164:165], off
	v_lshl_add_u64 v[164:165], s[44:45], 0, v[148:149]
	s_add_i32 m0, s48, 0x2000
	s_nop 0
	global_load_lds_dwordx4 v[164:165], off
	v_lshl_add_u64 v[164:165], v[240:241], 0, s[84:85]
	s_mov_b32 m0, s54
	s_nop 0
	global_load_lds_dwordx4 v[164:165], off
	v_lshl_add_u64 v[164:165], v[242:243], 0, s[84:85]
	s_mov_b32 m0, s55
	s_nop 0
	global_load_lds_dwordx4 v[164:165], off
	s_waitcnt vmcnt(8)
	s_waitcnt lgkmcnt(0)
	s_barrier
	s_setprio 1
	s_waitcnt lgkmcnt(0)
	v_mfma_i32_16x16x64_i8 v[72:75], v[60:63], v[184:187], v[72:75]
	v_mfma_i32_16x16x64_i8 v[72:75], v[68:71], v[188:191], v[72:75]
	v_mfma_i32_16x16x64_i8 v[56:59], v[68:71], v[208:211], v[56:59]
	v_mfma_i32_16x16x64_i8 v[56:59], v[60:63], v[204:207], v[56:59]
	v_mfma_i32_16x16x64_i8 v[32:35], v[60:63], v[212:215], v[32:35]
	v_mfma_i32_16x16x64_i8 v[32:35], v[68:71], v[216:219], v[32:35]
	v_mfma_i32_16x16x64_i8 v[16:19], v[68:71], v[224:227], v[16:19]
	v_mfma_i32_16x16x64_i8 v[16:19], v[60:63], v[220:223], v[16:19]
	v_mfma_i32_16x16x64_i8 v[64:67], v[140:143], v[184:187], v[64:67]
	v_mfma_i32_16x16x64_i8 v[64:67], v[144:147], v[188:191], v[64:67]
	v_mfma_i32_16x16x64_i8 v[48:51], v[144:147], v[208:211], v[48:51]
	v_mfma_i32_16x16x64_i8 v[48:51], v[140:143], v[204:207], v[48:51]
	v_mfma_i32_16x16x64_i8 v[24:27], v[140:143], v[212:215], v[24:27]
	v_mfma_i32_16x16x64_i8 v[24:27], v[144:147], v[216:219], v[24:27]
	v_mfma_i32_16x16x64_i8 v[8:11], v[144:147], v[224:227], v[8:11]
	v_mfma_i32_16x16x64_i8 v[8:11], v[140:143], v[220:223], v[8:11]
	s_setprio 0
	s_setprio 1
	v_mfma_i32_16x16x64_i8 v[36:39], v[160:163], v[184:187], v[36:39]
	v_mfma_i32_16x16x64_i8 v[68:71], v[172:175], v[188:191], v[36:39]
	v_mfma_i32_16x16x64_i8 v[36:39], v[172:175], v[208:211], v[52:55]
	v_mfma_i32_16x16x64_i8 v[52:55], v[160:163], v[204:207], v[36:39]
	v_mfma_i32_16x16x64_i8 v[28:31], v[160:163], v[212:215], v[28:31]
	v_mfma_i32_16x16x64_i8 v[28:31], v[172:175], v[216:219], v[28:31]
	v_mfma_i32_16x16x64_i8 v[12:15], v[172:175], v[224:227], v[12:15]
	v_mfma_i32_16x16x64_i8 v[12:15], v[160:163], v[220:223], v[12:15]
	v_mfma_i32_16x16x64_i8 v[36:39], v[176:179], v[184:187], v[44:47]
	v_mfma_i32_16x16x64_i8 v[60:63], v[180:183], v[188:191], v[36:39]
	v_mfma_i32_16x16x64_i8 v[36:39], v[180:183], v[208:211], v[40:43]
	v_mfma_i32_16x16x64_i8 v[40:43], v[176:179], v[204:207], v[36:39]
	v_mfma_i32_16x16x64_i8 v[20:23], v[176:179], v[212:215], v[20:23]
	v_mfma_i32_16x16x64_i8 v[20:23], v[180:183], v[216:219], v[20:23]
	v_mfma_i32_16x16x64_i8 v[4:7], v[180:183], v[224:227], v[4:7]
	v_mfma_i32_16x16x64_i8 v[4:7], v[176:179], v[220:223], v[4:7]
	s_setprio 0
	s_barrier
	s_add_i32 s61, s61, 2
	s_add_u32 s40, s40, 0x100
	s_addc_u32 s41, s41, 0
	s_add_u32 s59, s59, 0x100
	s_addc_u32 s60, s60, 0
	s_cmp_gt_u32 s61, 29
	s_cbranch_scc1 .Lkloop_exit_3
.LBB0_1591:
	s_add_u32 s44, s40, 0xfff80080
	s_addc_u32 s45, s41, -1
	s_add_i32 s64, 0, 0x10000
	s_cmp_eq_u32 s61, 28
	s_cselect_b32 s49, s25, s45
	s_cselect_b32 s48, s57, s44
	s_cselect_b32 s45, s23, s60
	s_cselect_b32 s44, s58, s59
	s_add_i32 s67, 0, 0x14000
	v_add_u32_e32 v144, s64, v167
	v_add_u32_e32 v158, s67, v167
	ds_read_b128 v[36:39], v144
	ds_read_b128 v[44:47], v144 offset:1024
	ds_read_b128 v[140:143], v144 offset:2048
	ds_read_b128 v[144:147], v144 offset:3072
	ds_read_b128 v[160:163], v158
	ds_read_b128 v[172:175], v158 offset:1024
	ds_read_b128 v[176:179], v158 offset:2048
	ds_read_b128 v[180:183], v158 offset:3072
	v_lshl_add_u64 v[164:165], s[40:41], 0, v[154:155]
	s_add_i32 m0, s50, 0xc000
	ds_read_b128 v[184:187], v171
	ds_read_b128 v[188:191], v171 offset:1024
	ds_read_b128 v[204:207], v171 offset:2048
	ds_read_b128 v[208:211], v171 offset:3072
	ds_read_b128 v[212:215], v171 offset:4096
	ds_read_b128 v[216:219], v171 offset:5120
	ds_read_b128 v[220:223], v171 offset:6144
	ds_read_b128 v[224:227], v171 offset:7168
	global_load_lds_dwordx4 v[164:165], off
	v_lshl_add_u64 v[164:165], s[40:41], 0, v[156:157]
	s_add_i32 m0, s50, 0xe000
	s_nop 0
	global_load_lds_dwordx4 v[164:165], off
	s_waitcnt vmcnt(8)
	s_waitcnt lgkmcnt(0)
	s_barrier
; #define PG8_STAGE(bufoff, gbase, voff) do { _Pragma("unroll") for (int _i = 0; _i < 2; ++_i) \
;         __builtin_amdgcn_global_load_lds((const unsigned*)((const char*)(gbase) + (voff)[_i]), (PG8_LAS unsigned*)(lds + (bufoff) + ldsw + _i * 8192), 16, 0, 0); } while (0)
; #define PG8_LDA(dst, b, h) do { _Pragma("unroll") for (int m = 0; m < 4; ++m) _Pragma("unroll") for (int k = 0; k < 2; ++k) dst[m][k] = *(const PG8_LAS bf16x8*)(lds + PG8_SA(b, h) + aoff + m * 2048 + k * 1024); } while (0)
; #define PG8_WAIT_V(n) asm volatile("s_waitcnt vmcnt(" #n ")" ::: "memory")
; #define PG8_WAIT_L(n) asm volatile("s_waitcnt lgkmcnt(" #n ")" ::: "memory")
; #define PG8_BAR __builtin_amdgcn_s_barrier()
; #define PG8_SCHED __builtin_amdgcn_sched_barrier(0)
; template <class Epi, class Sched, bool ALIGN_EPI = false, bool SP2 = false, bool I8 = false>
; __device__ __forceinline__ void gemm_phase(PG8_LAS unsigned char* lds, const Gemm g, const Sched& S, const Epi& E) {
;     ...
;             PG8_WAIT_V(8); PG8_WAIT_L(0); PG8_BAR; PG8_MMA(0, 0, At, B0); PG8_MMA(0, 1, At, B1); PG8_BAR; PG8_SCHED;
;             PG8_LDA(At, 0, 1); PG8_STAGE(PG8_SB(0, 0), b2, voffB); PG8_STAGE(PG8_SB(0, 1), b2 + hstep, voffB); PG8_STAGE(PG8_SA(0, 0), a2, voffA);
;             PG8_WAIT_V(8); PG8_WAIT_L(0); PG8_BAR; PG8_MMA(1, 0, At, B0); PG8_MMA(1, 1, At, B1); PG8_BAR; PG8_SCHED;
	s_setprio 1
	s_waitcnt lgkmcnt(0)
	v_mfma_i32_16x16x64_i8 v[136:139], v[36:39], v[184:187], v[136:139]
	v_mfma_i32_16x16x64_i8 v[136:139], v[44:47], v[188:191], v[136:139]
	v_mfma_i32_16x16x64_i8 v[120:123], v[44:47], v[208:211], v[120:123]
	v_mfma_i32_16x16x64_i8 v[120:123], v[36:39], v[204:207], v[120:123]
	v_mfma_i32_16x16x64_i8 v[104:107], v[36:39], v[212:215], v[104:107]
	v_mfma_i32_16x16x64_i8 v[104:107], v[44:47], v[216:219], v[104:107]
	v_mfma_i32_16x16x64_i8 v[88:91], v[44:47], v[224:227], v[88:91]
	v_mfma_i32_16x16x64_i8 v[88:91], v[36:39], v[220:223], v[88:91]
	v_mfma_i32_16x16x64_i8 v[128:131], v[140:143], v[184:187], v[128:131]
	v_mfma_i32_16x16x64_i8 v[128:131], v[144:147], v[188:191], v[128:131]
	v_mfma_i32_16x16x64_i8 v[112:115], v[144:147], v[208:211], v[112:115]
	v_mfma_i32_16x16x64_i8 v[112:115], v[140:143], v[204:207], v[112:115]
	v_mfma_i32_16x16x64_i8 v[96:99], v[140:143], v[212:215], v[96:99]
	v_mfma_i32_16x16x64_i8 v[96:99], v[144:147], v[216:219], v[96:99]
	v_mfma_i32_16x16x64_i8 v[80:83], v[144:147], v[224:227], v[80:83]
	v_mfma_i32_16x16x64_i8 v[80:83], v[140:143], v[220:223], v[80:83]
	s_setprio 0
	s_setprio 1
	v_mfma_i32_16x16x64_i8 v[132:135], v[160:163], v[184:187], v[132:135]
	v_mfma_i32_16x16x64_i8 v[132:135], v[172:175], v[188:191], v[132:135]
	v_mfma_i32_16x16x64_i8 v[116:119], v[172:175], v[208:211], v[116:119]
	v_mfma_i32_16x16x64_i8 v[116:119], v[160:163], v[204:207], v[116:119]
	v_mfma_i32_16x16x64_i8 v[100:103], v[160:163], v[212:215], v[100:103]
	v_mfma_i32_16x16x64_i8 v[100:103], v[172:175], v[216:219], v[100:103]
	v_mfma_i32_16x16x64_i8 v[84:87], v[172:175], v[224:227], v[84:87]
	v_mfma_i32_16x16x64_i8 v[84:87], v[160:163], v[220:223], v[84:87]
	v_mfma_i32_16x16x64_i8 v[124:127], v[176:179], v[184:187], v[124:127]
	v_mfma_i32_16x16x64_i8 v[124:127], v[180:183], v[188:191], v[124:127]
	v_mfma_i32_16x16x64_i8 v[108:111], v[180:183], v[208:211], v[108:111]
	v_mfma_i32_16x16x64_i8 v[108:111], v[176:179], v[204:207], v[108:111]
	v_mfma_i32_16x16x64_i8 v[92:95], v[176:179], v[212:215], v[92:95]
	v_mfma_i32_16x16x64_i8 v[92:95], v[180:183], v[216:219], v[92:95]
	v_mfma_i32_16x16x64_i8 v[76:79], v[180:183], v[224:227], v[76:79]
	v_mfma_i32_16x16x64_i8 v[76:79], v[176:179], v[220:223], v[76:79]
	s_setprio 0
	s_barrier
	s_add_i32 s64, s64, s47
	v_lshl_add_u64 v[164:165], s[44:45], 0, v[2:3]
	s_mov_b32 m0, s64
	ds_read_b128 v[184:187], v171 offset:16384
	ds_read_b128 v[188:191], v171 offset:17408
	ds_read_b128 v[204:207], v171 offset:18432
	ds_read_b128 v[208:211], v171 offset:19456
	ds_read_b128 v[212:215], v171 offset:20480
	ds_read_b128 v[216:219], v171 offset:21504
	ds_read_b128 v[220:223], v171 offset:22528
	ds_read_b128 v[224:227], v171 offset:23552
	global_load_lds_dwordx4 v[164:165], off
	s_add_i32 m0, s64, 0x2000
	s_add_u32 s64, s44, 0x80000
	v_lshl_add_u64 v[228:229], s[44:45], 0, v[148:149]
	s_addc_u32 s65, s45, 0
	s_add_i32 s67, s67, s47
	global_load_lds_dwordx4 v[228:229], off
	v_lshl_add_u64 v[240:241], s[64:65], 0, v[2:3]
	s_mov_b32 m0, s67
	v_lshl_add_u64 v[242:243], s[48:49], 0, v[150:151]
	global_load_lds_dwordx4 v[240:241], off
	v_lshl_add_u64 v[240:241], s[64:65], 0, v[148:149]
	s_add_i32 m0, s67, 0x2000
	s_nop 0
	global_load_lds_dwordx4 v[240:241], off
	v_lshl_add_u64 v[240:241], s[48:49], 0, v[152:153]
	s_mov_b32 m0, s50
	s_nop 0
	global_load_lds_dwordx4 v[240:241], off
	s_mov_b32 m0, s51
	s_nop 0
	global_load_lds_dwordx4 v[242:243], off
	s_waitcnt vmcnt(8)
	s_waitcnt lgkmcnt(0)
	s_barrier
	s_setprio 1
	s_waitcnt lgkmcnt(0)
	v_mfma_i32_16x16x64_i8 v[72:75], v[36:39], v[184:187], v[72:75]
	v_mfma_i32_16x16x64_i8 v[72:75], v[44:47], v[188:191], v[72:75]
	v_mfma_i32_16x16x64_i8 v[56:59], v[44:47], v[208:211], v[56:59]
	v_mfma_i32_16x16x64_i8 v[56:59], v[36:39], v[204:207], v[56:59]
	v_mfma_i32_16x16x64_i8 v[32:35], v[36:39], v[212:215], v[32:35]
	v_mfma_i32_16x16x64_i8 v[32:35], v[44:47], v[216:219], v[32:35]
	v_mfma_i32_16x16x64_i8 v[16:19], v[44:47], v[224:227], v[16:19]
	v_mfma_i32_16x16x64_i8 v[16:19], v[36:39], v[220:223], v[16:19]
	v_mfma_i32_16x16x64_i8 v[64:67], v[140:143], v[184:187], v[64:67]
	v_mfma_i32_16x16x64_i8 v[64:67], v[144:147], v[188:191], v[64:67]
	v_mfma_i32_16x16x64_i8 v[48:51], v[144:147], v[208:211], v[48:51]
	v_mfma_i32_16x16x64_i8 v[48:51], v[140:143], v[204:207], v[48:51]
	v_mfma_i32_16x16x64_i8 v[24:27], v[140:143], v[212:215], v[24:27]
	v_mfma_i32_16x16x64_i8 v[24:27], v[144:147], v[216:219], v[24:27]
	v_mfma_i32_16x16x64_i8 v[8:11], v[144:147], v[224:227], v[8:11]
	v_mfma_i32_16x16x64_i8 v[8:11], v[140:143], v[220:223], v[8:11]
	s_setprio 0
	s_setprio 1
	v_mfma_i32_16x16x64_i8 v[52:55], v[160:163], v[204:207], v[52:55]
	v_mfma_i32_16x16x64_i8 v[52:55], v[172:175], v[208:211], v[52:55]
	v_mfma_i32_16x16x64_i8 v[28:31], v[172:175], v[216:219], v[28:31]
	v_mfma_i32_16x16x64_i8 v[28:31], v[160:163], v[212:215], v[28:31]
	v_mfma_i32_16x16x64_i8 v[12:15], v[160:163], v[220:223], v[12:15]
	v_mfma_i32_16x16x64_i8 v[12:15], v[172:175], v[224:227], v[12:15]
	v_mfma_i32_16x16x64_i8 v[36:39], v[172:175], v[188:191], v[68:71]
	v_mfma_i32_16x16x64_i8 v[36:39], v[160:163], v[184:187], v[36:39]
	v_mfma_i32_16x16x64_i8 v[40:43], v[176:179], v[204:207], v[40:43]
	v_mfma_i32_16x16x64_i8 v[40:43], v[180:183], v[208:211], v[40:43]
	v_mfma_i32_16x16x64_i8 v[20:23], v[180:183], v[216:219], v[20:23]
	v_mfma_i32_16x16x64_i8 v[20:23], v[176:179], v[212:215], v[20:23]
	v_mfma_i32_16x16x64_i8 v[4:7], v[176:179], v[220:223], v[4:7]
	v_mfma_i32_16x16x64_i8 v[4:7], v[180:183], v[224:227], v[4:7]
	v_mfma_i32_16x16x64_i8 v[44:47], v[180:183], v[188:191], v[60:63]
	v_mfma_i32_16x16x64_i8 v[44:47], v[176:179], v[184:187], v[44:47]
	s_setprio 0
	s_barrier
; #define PG8_STAGE(bufoff, gbase, voff) do { _Pragma("unroll") for (int _i = 0; _i < 2; ++_i) \
;         __builtin_amdgcn_global_load_lds((const unsigned*)((const char*)(gbase) + (voff)[_i]), (PG8_LAS unsigned*)(lds + (bufoff) + ldsw + _i * 8192), 16, 0, 0); } while (0)
; #define PG8_LDA(dst, b, h) do { _Pragma("unroll") for (int m = 0; m < 4; ++m) _Pragma("unroll") for (int k = 0; k < 2; ++k) dst[m][k] = *(const PG8_LAS bf16x8*)(lds + PG8_SA(b, h) + aoff + m * 2048 + k * 1024); } while (0)
; #define PG8_LDB(dst, b, h) do { _Pragma("unroll") for (int n = 0; n < 2; ++n) _Pragma("unroll") for (int k = 0; k < 2; ++k) dst[n][k] = *(const PG8_LAS bf16x8*)(lds + PG8_SB(b, h) + boff + n * 2048 + k * 1024); } while (0)
; #define PG8_WAIT_V(n) asm volatile("s_waitcnt vmcnt(" #n ")" ::: "memory")
; #define PG8_WAIT_L(n) asm volatile("s_waitcnt lgkmcnt(" #n ")" ::: "memory")
; #define PG8_BAR __builtin_amdgcn_s_barrier()
; #define PG8_SCHED __builtin_amdgcn_sched_barrier(0)
; template <class Epi, class Sched, bool ALIGN_EPI = false, bool SP2 = false, bool I8 = false>
; __device__ __forceinline__ void gemm_phase(PG8_LAS unsigned char* lds, const Gemm g, const Sched& S, const Epi& E) {
;     ...
;             PG8_LDB(B0, 1, 0); PG8_LDB(B1, 1, 1); PG8_SCHED; PG8_LDA(At, 1, 0); PG8_STAGE(PG8_SA(0, 1), a2 + hstep, voffA);
;             PG8_WAIT_V(8); PG8_WAIT_L(0); PG8_BAR; PG8_MMA(0, 0, At, B0); PG8_MMA(0, 1, At, B1); PG8_BAR; PG8_SCHED;
;             PG8_LDA(At, 1, 1); PG8_STAGE(PG8_SB(1, 0), b3, voffB); PG8_STAGE(PG8_SB(1, 1), b3 + hstep, voffB); PG8_STAGE(PG8_SA(1, 0), a3, voffA);
;             PG8_WAIT_V(8); PG8_WAIT_L(0); PG8_BAR; PG8_MMA(1, 0, At, B0); PG8_MMA(1, 1, At, B1); PG8_BAR; PG8_SCHED;
	s_add_i32 s64, 0, 0x18000
	s_add_i32 s65, 0, 0x1c000
	v_add_u32_e32 v144, s64, v167
	v_add_u32_e32 v158, s65, v167
	ds_read_b128 v[60:63], v144
	ds_read_b128 v[68:71], v144 offset:1024
	ds_read_b128 v[140:143], v144 offset:2048
	ds_read_b128 v[144:147], v144 offset:3072
	ds_read_b128 v[160:163], v158
	ds_read_b128 v[172:175], v158 offset:1024
	ds_read_b128 v[176:179], v158 offset:2048
	ds_read_b128 v[180:183], v158 offset:3072
	s_add_u32 s48, s48, 0x80000
	s_addc_u32 s49, s49, 0
	s_mov_b32 m0, s52
	v_lshl_add_u64 v[244:245], s[48:49], 0, v[152:153]
	ds_read_b128 v[184:187], v171 offset:32768
	ds_read_b128 v[188:191], v171 offset:33792
	ds_read_b128 v[204:207], v171 offset:34816
	ds_read_b128 v[208:211], v171 offset:35840
	ds_read_b128 v[212:215], v171 offset:36864
	ds_read_b128 v[216:219], v171 offset:37888
	ds_read_b128 v[220:223], v171 offset:38912
	ds_read_b128 v[224:227], v171 offset:39936
	global_load_lds_dwordx4 v[244:245], off
	v_lshl_add_u64 v[244:245], s[48:49], 0, v[150:151]
	s_mov_b32 m0, s53
	s_nop 0
	global_load_lds_dwordx4 v[244:245], off
	s_waitcnt vmcnt(8)
	s_waitcnt lgkmcnt(0)
	s_barrier
	s_setprio 1
	s_waitcnt lgkmcnt(0)
	v_mfma_i32_16x16x64_i8 v[136:139], v[60:63], v[184:187], v[136:139]
	v_mfma_i32_16x16x64_i8 v[136:139], v[68:71], v[188:191], v[136:139]
	v_mfma_i32_16x16x64_i8 v[120:123], v[68:71], v[208:211], v[120:123]
	v_mfma_i32_16x16x64_i8 v[120:123], v[60:63], v[204:207], v[120:123]
	v_mfma_i32_16x16x64_i8 v[104:107], v[60:63], v[212:215], v[104:107]
	v_mfma_i32_16x16x64_i8 v[104:107], v[68:71], v[216:219], v[104:107]
	v_mfma_i32_16x16x64_i8 v[88:91], v[68:71], v[224:227], v[88:91]
	v_mfma_i32_16x16x64_i8 v[88:91], v[60:63], v[220:223], v[88:91]
	v_mfma_i32_16x16x64_i8 v[128:131], v[140:143], v[184:187], v[128:131]
	v_mfma_i32_16x16x64_i8 v[128:131], v[144:147], v[188:191], v[128:131]
	v_mfma_i32_16x16x64_i8 v[112:115], v[144:147], v[208:211], v[112:115]
	v_mfma_i32_16x16x64_i8 v[112:115], v[140:143], v[204:207], v[112:115]
	v_mfma_i32_16x16x64_i8 v[96:99], v[140:143], v[212:215], v[96:99]
	v_mfma_i32_16x16x64_i8 v[96:99], v[144:147], v[216:219], v[96:99]
	v_mfma_i32_16x16x64_i8 v[80:83], v[144:147], v[224:227], v[80:83]
	v_mfma_i32_16x16x64_i8 v[80:83], v[140:143], v[220:223], v[80:83]
	s_setprio 0
	s_setprio 1
	v_mfma_i32_16x16x64_i8 v[132:135], v[160:163], v[184:187], v[132:135]
	v_mfma_i32_16x16x64_i8 v[132:135], v[172:175], v[188:191], v[132:135]
	v_mfma_i32_16x16x64_i8 v[116:119], v[172:175], v[208:211], v[116:119]
	v_mfma_i32_16x16x64_i8 v[116:119], v[160:163], v[204:207], v[116:119]
	v_mfma_i32_16x16x64_i8 v[100:103], v[160:163], v[212:215], v[100:103]
	v_mfma_i32_16x16x64_i8 v[100:103], v[172:175], v[216:219], v[100:103]
	v_mfma_i32_16x16x64_i8 v[84:87], v[172:175], v[224:227], v[84:87]
	v_mfma_i32_16x16x64_i8 v[84:87], v[160:163], v[220:223], v[84:87]
	v_mfma_i32_16x16x64_i8 v[124:127], v[176:179], v[184:187], v[124:127]
	v_mfma_i32_16x16x64_i8 v[124:127], v[180:183], v[188:191], v[124:127]
	v_mfma_i32_16x16x64_i8 v[108:111], v[180:183], v[208:211], v[108:111]
	v_mfma_i32_16x16x64_i8 v[108:111], v[176:179], v[204:207], v[108:111]
	v_mfma_i32_16x16x64_i8 v[92:95], v[176:179], v[212:215], v[92:95]
	v_mfma_i32_16x16x64_i8 v[92:95], v[180:183], v[216:219], v[92:95]
	v_mfma_i32_16x16x64_i8 v[76:79], v[180:183], v[224:227], v[76:79]
	v_mfma_i32_16x16x64_i8 v[76:79], v[176:179], v[220:223], v[76:79]
	s_setprio 0
	s_barrier
	s_add_i32 s48, s64, s47
	v_lshl_add_u64 v[164:165], v[164:165], 0, s[84:85]
	s_mov_b32 m0, s48
	ds_read_b128 v[184:187], v171 offset:49152
	ds_read_b128 v[188:191], v171 offset:50176
	ds_read_b128 v[204:207], v171 offset:51200
	ds_read_b128 v[208:211], v171 offset:52224
	ds_read_b128 v[212:215], v171 offset:53248
	ds_read_b128 v[216:219], v171 offset:54272
	ds_read_b128 v[220:223], v171 offset:55296
	ds_read_b128 v[224:227], v171 offset:56320
	global_load_lds_dwordx4 v[164:165], off
	s_add_i32 m0, s48, 0x2000
	s_add_u32 s44, s44, 0x80080
	v_lshl_add_u64 v[164:165], v[228:229], 0, s[84:85]
	s_addc_u32 s45, s45, 0
	s_add_i32 s48, s65, s47
	global_load_lds_dwordx4 v[164:165], off
	v_lshl_add_u64 v[164:165], s[44:45], 0, v[2:3]
	s_mov_b32 m0, s48
	s_nop 0
	global_load_lds_dwordx4 v[164:165], off
	v_lshl_add_u64 v[164:165], s[44:45], 0, v[148:149]
	s_add_i32 m0, s48, 0x2000
	s_nop 0
	global_load_lds_dwordx4 v[164:165], off
	v_lshl_add_u64 v[164:165], v[240:241], 0, s[84:85]
	s_mov_b32 m0, s54
	s_nop 0
	global_load_lds_dwordx4 v[164:165], off
	v_lshl_add_u64 v[164:165], v[242:243], 0, s[84:85]
	s_mov_b32 m0, s55
	s_nop 0
	global_load_lds_dwordx4 v[164:165], off
	s_waitcnt vmcnt(8)
	s_waitcnt lgkmcnt(0)
	s_barrier
	s_setprio 1
	s_waitcnt lgkmcnt(0)
	v_mfma_i32_16x16x64_i8 v[72:75], v[60:63], v[184:187], v[72:75]
	v_mfma_i32_16x16x64_i8 v[72:75], v[68:71], v[188:191], v[72:75]
	v_mfma_i32_16x16x64_i8 v[56:59], v[68:71], v[208:211], v[56:59]
	v_mfma_i32_16x16x64_i8 v[56:59], v[60:63], v[204:207], v[56:59]
	v_mfma_i32_16x16x64_i8 v[32:35], v[60:63], v[212:215], v[32:35]
	v_mfma_i32_16x16x64_i8 v[32:35], v[68:71], v[216:219], v[32:35]
	v_mfma_i32_16x16x64_i8 v[16:19], v[68:71], v[224:227], v[16:19]
	v_mfma_i32_16x16x64_i8 v[16:19], v[60:63], v[220:223], v[16:19]
	v_mfma_i32_16x16x64_i8 v[64:67], v[140:143], v[184:187], v[64:67]
	v_mfma_i32_16x16x64_i8 v[64:67], v[144:147], v[188:191], v[64:67]
	v_mfma_i32_16x16x64_i8 v[48:51], v[144:147], v[208:211], v[48:51]
	v_mfma_i32_16x16x64_i8 v[48:51], v[140:143], v[204:207], v[48:51]
	v_mfma_i32_16x16x64_i8 v[24:27], v[140:143], v[212:215], v[24:27]
	v_mfma_i32_16x16x64_i8 v[24:27], v[144:147], v[216:219], v[24:27]
	v_mfma_i32_16x16x64_i8 v[8:11], v[144:147], v[224:227], v[8:11]
	v_mfma_i32_16x16x64_i8 v[8:11], v[140:143], v[220:223], v[8:11]
	s_setprio 0
	s_setprio 1
	v_mfma_i32_16x16x64_i8 v[36:39], v[160:163], v[184:187], v[36:39]
	v_mfma_i32_16x16x64_i8 v[68:71], v[172:175], v[188:191], v[36:39]
	v_mfma_i32_16x16x64_i8 v[36:39], v[172:175], v[208:211], v[52:55]
	v_mfma_i32_16x16x64_i8 v[52:55], v[160:163], v[204:207], v[36:39]
	v_mfma_i32_16x16x64_i8 v[28:31], v[160:163], v[212:215], v[28:31]
	v_mfma_i32_16x16x64_i8 v[28:31], v[172:175], v[216:219], v[28:31]
	v_mfma_i32_16x16x64_i8 v[12:15], v[172:175], v[224:227], v[12:15]
	v_mfma_i32_16x16x64_i8 v[12:15], v[160:163], v[220:223], v[12:15]
	v_mfma_i32_16x16x64_i8 v[36:39], v[176:179], v[184:187], v[44:47]
	v_mfma_i32_16x16x64_i8 v[60:63], v[180:183], v[188:191], v[36:39]
	v_mfma_i32_16x16x64_i8 v[36:39], v[180:183], v[208:211], v[40:43]
	v_mfma_i32_16x16x64_i8 v[40:43], v[176:179], v[204:207], v[36:39]
	v_mfma_i32_16x16x64_i8 v[20:23], v[176:179], v[212:215], v[20:23]
	v_mfma_i32_16x16x64_i8 v[20:23], v[180:183], v[216:219], v[20:23]
	v_mfma_i32_16x16x64_i8 v[4:7], v[180:183], v[224:227], v[4:7]
	v_mfma_i32_16x16x64_i8 v[4:7], v[176:179], v[220:223], v[4:7]
	s_setprio 0
	s_barrier
	s_add_i32 s61, s61, 2
	s_add_u32 s40, s40, 0x100
	s_addc_u32 s41, s41, 0
	s_add_u32 s59, s59, 0x100
	s_addc_u32 s60, s60, 0
	s_cmp_gt_u32 s61, 29
	s_cbranch_scc0 .LBB0_1591

; #define PG8_STAGE(bufoff, gbase, voff) do { _Pragma("unroll") for (int _i = 0; _i < 2; ++_i) \
;         __builtin_amdgcn_global_load_lds((const unsigned*)((const char*)(gbase) + (voff)[_i]), (PG8_LAS unsigned*)(lds + (bufoff) + ldsw + _i * 8192), 16, 0, 0); } while (0)
; #define PG8_LDA(dst, b, h) do { _Pragma("unroll") for (int m = 0; m < 4; ++m) _Pragma("unroll") for (int k = 0; k < 2; ++k) dst[m][k] = *(const PG8_LAS bf16x8*)(lds + PG8_SA(b, h) + aoff + m * 2048 + k * 1024); } while (0)
; #define PG8_LDB(dst, b, h) do { _Pragma("unroll") for (int n = 0; n < 2; ++n) _Pragma("unroll") for (int k = 0; k < 2; ++k) dst[n][k] = *(const PG8_LAS bf16x8*)(lds + PG8_SB(b, h) + boff + n * 2048 + k * 1024); } while (0)
; #define PG8_WAIT_V(n) asm volatile("s_waitcnt vmcnt(" #n ")" ::: "memory")
; #define PG8_WAIT_L(n) asm volatile("s_waitcnt lgkmcnt(" #n ")" ::: "memory")
; #define PG8_BAR __builtin_amdgcn_s_barrier()
; #define PG8_SCHED __builtin_amdgcn_sched_barrier(0)
; template <class Epi, class Sched, bool ALIGN_EPI = false, bool SP2 = false, bool I8 = false>
; __device__ __forceinline__ void gemm_phase(PG8_LAS unsigned char* lds, const Gemm g, const Sched& S, const Epi& E) {
;     ...
;         const bool has_next = S.next(ui + 1, nxt);
;         const char* nA = has_next ? (const char*)g.A + (size_t)nxt.pm * tstep : cA; const char* nB = has_next ? (const char*)g.Bt + (size_t)nxt.pn * tstep : cB;
;         for (int t = 0; t < nt; t += 2) {
;             const bool last = (t == nt - 2);
;             const char* a1 = cA + (size_t)(t + 1) * kstep;
;             const char* a2 = last ? nA : cA + (size_t)(t + 2) * kstep; const char* b2 = last ? nB : cB + (size_t)(t + 2) * kstep;
;             const char* a3 = a2 + kstep; const char* b3 = b2 + kstep;
;             if (last && has_next) S.a_ready(nxt);
;             if constexpr (SP2) {
;             PG8_LDB(B0, 0, 0); PG8_LDB(B1, 0, 1); PG8_SCHED; PG8_LDA(At, 0, 0); PG8_STAGE(PG8_SA(1, 1), a1 + hstep, voffA);
;             PG8_WAIT_V(8); PG8_WAIT_L(0); PG8_BAR; PG8_MMA(0, 0, At, B0); PG8_MMA(0, 1, At, B1); PG8_BAR; PG8_SCHED;
;             PG8_LDA(At, 0, 1); PG8_STAGE(PG8_SB(0, 0), b2, voffB); PG8_STAGE(PG8_SB(0, 1), b2 + hstep, voffB); PG8_STAGE(PG8_SA(0, 0), a2, voffA);
.LBB0_1842:
	s_ashr_i32 s45, s44, 31
	s_lshl_b64 s[34:35], s[44:45], 20
	s_add_u32 s50, s47, s34
	s_addc_u32 s51, s52, s35
	s_and_b64 s[34:35], s[8:9], exec
	s_cselect_b32 s11, s51, s55
	s_cselect_b32 s13, s50, s54
	s_ashr_i32 s49, s48, 31
	s_lshl_b64 s[34:35], s[48:49], 20
	s_add_u32 s56, s53, s34
	s_addc_u32 s57, s64, s35
	s_and_b64 s[34:35], s[8:9], exec
	s_cselect_b32 s34, s57, s59
	s_cselect_b32 s35, s56, s58
	s_add_u32 s54, s54, 0x80080
	s_addc_u32 s55, s55, 0
	s_add_u32 s45, s58, 0x100
	s_addc_u32 s49, s59, 0
	s_mov_b32 s86, -2
	s_waitcnt lgkmcnt(0)
	s_add_u32 s58, s54, 0xfff80080
	s_addc_u32 s59, s55, -1
	s_add_i32 s87, 0, 0x10000
	s_cmp_eq_u32 s86, 28
	s_cselect_b32 s61, s11, s59
	s_cselect_b32 s60, s13, s58
	s_cselect_b32 s59, s34, s49
	s_cselect_b32 s58, s35, s45
	s_add_i32 vcc_lo, 0, 0x14000
	v_add_u32_e32 v40, s87, v217
	v_add_u32_e32 v160, vcc_lo, v217
	ds_read_b128 v[28:31], v40
	ds_read_b128 v[32:35], v40 offset:1024
	ds_read_b128 v[36:39], v40 offset:2048
	ds_read_b128 v[40:43], v40 offset:3072
	ds_read_b128 v[140:143], v160
	ds_read_b128 v[144:147], v160 offset:1024
	ds_read_b128 v[156:159], v160 offset:2048
	ds_read_b128 v[160:163], v160 offset:3072
	v_lshl_add_u64 v[190:191], s[54:55], 0, v[186:187]
	s_add_i32 m0, s65, 0xc000
	ds_read_b128 v[164:167], v219
	ds_read_b128 v[168:171], v219 offset:1024
	ds_read_b128 v[172:175], v219 offset:2048
	ds_read_b128 v[176:179], v219 offset:3072
	ds_read_b128 v[204:207], v219 offset:4096
	ds_read_b128 v[208:211], v219 offset:5120
	ds_read_b128 v[212:215], v219 offset:6144
	ds_read_b128 v[220:223], v219 offset:7168
	global_load_lds_dwordx4 v[190:191], off
	v_lshl_add_u64 v[190:191], s[54:55], 0, v[188:189]
	s_add_i32 m0, s65, 0xe000
	s_nop 0
	global_load_lds_dwordx4 v[190:191], off
	s_waitcnt vmcnt(8)
	s_waitcnt lgkmcnt(0)
	s_barrier
	s_setprio 1
	s_waitcnt lgkmcnt(0)
	v_mfma_i32_16x16x64_i8 v[152:155], v[28:31], v[164:167], 0
	v_mfma_i32_16x16x64_i8 v[152:155], v[32:35], v[168:171], v[152:155]
	v_mfma_i32_16x16x64_i8 v[128:131], v[32:35], v[176:179], 0
	v_mfma_i32_16x16x64_i8 v[128:131], v[28:31], v[172:175], v[128:131]
	v_mfma_i32_16x16x64_i8 v[112:115], v[28:31], v[204:207], 0
	v_mfma_i32_16x16x64_i8 v[112:115], v[32:35], v[208:211], v[112:115]
	v_mfma_i32_16x16x64_i8 v[96:99], v[32:35], v[220:223], 0
	v_mfma_i32_16x16x64_i8 v[96:99], v[28:31], v[212:215], v[96:99]
	v_mfma_i32_16x16x64_i8 v[148:151], v[36:39], v[164:167], 0
	v_mfma_i32_16x16x64_i8 v[148:151], v[40:43], v[168:171], v[148:151]
	v_mfma_i32_16x16x64_i8 v[124:127], v[40:43], v[176:179], 0
	v_mfma_i32_16x16x64_i8 v[124:127], v[36:39], v[172:175], v[124:127]
	v_mfma_i32_16x16x64_i8 v[108:111], v[36:39], v[204:207], 0
	v_mfma_i32_16x16x64_i8 v[108:111], v[40:43], v[208:211], v[108:111]
	v_mfma_i32_16x16x64_i8 v[92:95], v[40:43], v[220:223], 0
	v_mfma_i32_16x16x64_i8 v[92:95], v[36:39], v[212:215], v[92:95]
	s_setprio 0
	s_setprio 1
	v_mfma_i32_16x16x64_i8 v[136:139], v[140:143], v[164:167], 0
	v_mfma_i32_16x16x64_i8 v[136:139], v[144:147], v[168:171], v[136:139]
	v_mfma_i32_16x16x64_i8 v[120:123], v[144:147], v[176:179], 0
	v_mfma_i32_16x16x64_i8 v[120:123], v[140:143], v[172:175], v[120:123]
	v_mfma_i32_16x16x64_i8 v[104:107], v[140:143], v[204:207], 0
	v_mfma_i32_16x16x64_i8 v[104:107], v[144:147], v[208:211], v[104:107]
	v_mfma_i32_16x16x64_i8 v[88:91], v[144:147], v[220:223], 0
	v_mfma_i32_16x16x64_i8 v[88:91], v[140:143], v[212:215], v[88:91]
	v_mfma_i32_16x16x64_i8 v[132:135], v[156:159], v[164:167], 0
	v_mfma_i32_16x16x64_i8 v[132:135], v[160:163], v[168:171], v[132:135]
	v_mfma_i32_16x16x64_i8 v[116:119], v[160:163], v[176:179], 0
	v_mfma_i32_16x16x64_i8 v[116:119], v[156:159], v[172:175], v[116:119]
	v_mfma_i32_16x16x64_i8 v[100:103], v[156:159], v[204:207], 0
	v_mfma_i32_16x16x64_i8 v[100:103], v[160:163], v[208:211], v[100:103]
	v_mfma_i32_16x16x64_i8 v[84:87], v[160:163], v[220:223], 0
	v_mfma_i32_16x16x64_i8 v[84:87], v[156:159], v[212:215], v[84:87]
	s_setprio 0
	s_barrier
	s_add_i32 s87, s87, s46
	v_lshl_add_u64 v[190:191], s[58:59], 0, v[2:3]
	s_mov_b32 m0, s87
	ds_read_b128 v[164:167], v219 offset:16384
	ds_read_b128 v[168:171], v219 offset:17408
	ds_read_b128 v[172:175], v219 offset:18432
	ds_read_b128 v[176:179], v219 offset:19456
	ds_read_b128 v[204:207], v219 offset:20480
	ds_read_b128 v[208:211], v219 offset:21504
	ds_read_b128 v[212:215], v219 offset:22528
	ds_read_b128 v[220:223], v219 offset:23552
	global_load_lds_dwordx4 v[190:191], off
	s_add_i32 m0, s87, 0x2000
	s_add_u32 s96, s58, 0x80000
	v_lshl_add_u64 v[224:225], s[58:59], 0, v[184:185]
	s_addc_u32 s97, s59, 0
	s_add_i32 s87, vcc_lo, s46
	global_load_lds_dwordx4 v[224:225], off
	v_lshl_add_u64 v[226:227], s[96:97], 0, v[2:3]
	s_mov_b32 m0, s87
	v_lshl_add_u64 v[228:229], s[60:61], 0, v[182:183]
	global_load_lds_dwordx4 v[226:227], off
	v_lshl_add_u64 v[226:227], s[96:97], 0, v[184:185]
	s_add_i32 m0, s87, 0x2000
	s_nop 0
	global_load_lds_dwordx4 v[226:227], off
	v_lshl_add_u64 v[226:227], s[60:61], 0, v[180:181]
	s_mov_b32 m0, s65
	s_nop 0
	global_load_lds_dwordx4 v[226:227], off
	s_mov_b32 m0, s67
	s_nop 0
	global_load_lds_dwordx4 v[228:229], off
	s_waitcnt vmcnt(8)
	s_waitcnt lgkmcnt(0)
	s_barrier
; #define PG8_STAGE(bufoff, gbase, voff) do { _Pragma("unroll") for (int _i = 0; _i < 2; ++_i) \
;         __builtin_amdgcn_global_load_lds((const unsigned*)((const char*)(gbase) + (voff)[_i]), (PG8_LAS unsigned*)(lds + (bufoff) + ldsw + _i * 8192), 16, 0, 0); } while (0)
; #define PG8_LDA(dst, b, h) do { _Pragma("unroll") for (int m = 0; m < 4; ++m) _Pragma("unroll") for (int k = 0; k < 2; ++k) dst[m][k] = *(const PG8_LAS bf16x8*)(lds + PG8_SA(b, h) + aoff + m * 2048 + k * 1024); } while (0)
; #define PG8_LDB(dst, b, h) do { _Pragma("unroll") for (int n = 0; n < 2; ++n) _Pragma("unroll") for (int k = 0; k < 2; ++k) dst[n][k] = *(const PG8_LAS bf16x8*)(lds + PG8_SB(b, h) + boff + n * 2048 + k * 1024); } while (0)
; #define PG8_WAIT_V(n) asm volatile("s_waitcnt vmcnt(" #n ")" ::: "memory")
; #define PG8_WAIT_L(n) asm volatile("s_waitcnt lgkmcnt(" #n ")" ::: "memory")
; #define PG8_BAR __builtin_amdgcn_s_barrier()
; #define PG8_SCHED __builtin_amdgcn_sched_barrier(0)
; template <class Epi, class Sched, bool ALIGN_EPI = false, bool SP2 = false, bool I8 = false>
; __device__ __forceinline__ void gemm_phase(PG8_LAS unsigned char* lds, const Gemm g, const Sched& S, const Epi& E) {
;     ...
;             PG8_WAIT_V(8); PG8_WAIT_L(0); PG8_BAR; PG8_MMA(1, 0, At, B0); PG8_MMA(1, 1, At, B1); PG8_BAR; PG8_SCHED;
;             PG8_LDB(B0, 1, 0); PG8_LDB(B1, 1, 1); PG8_SCHED; PG8_LDA(At, 1, 0); PG8_STAGE(PG8_SA(0, 1), a2 + hstep, voffA);
;             PG8_WAIT_V(8); PG8_WAIT_L(0); PG8_BAR; PG8_MMA(0, 0, At, B0); PG8_MMA(0, 1, At, B1); PG8_BAR; PG8_SCHED;
	s_setprio 1
	s_waitcnt lgkmcnt(0)
	v_mfma_i32_16x16x64_i8 v[80:83], v[28:31], v[164:167], 0
	v_mfma_i32_16x16x64_i8 v[80:83], v[32:35], v[168:171], v[80:83]
	v_mfma_i32_16x16x64_i8 v[64:67], v[32:35], v[176:179], 0
	v_mfma_i32_16x16x64_i8 v[64:67], v[28:31], v[172:175], v[64:67]
	v_mfma_i32_16x16x64_i8 v[48:51], v[28:31], v[204:207], 0
	v_mfma_i32_16x16x64_i8 v[48:51], v[32:35], v[208:211], v[48:51]
	v_mfma_i32_16x16x64_i8 v[16:19], v[32:35], v[220:223], 0
	v_mfma_i32_16x16x64_i8 v[16:19], v[28:31], v[212:215], v[16:19]
	v_mfma_i32_16x16x64_i8 v[76:79], v[36:39], v[164:167], 0
	v_mfma_i32_16x16x64_i8 v[76:79], v[40:43], v[168:171], v[76:79]
	v_mfma_i32_16x16x64_i8 v[60:63], v[40:43], v[176:179], 0
	v_mfma_i32_16x16x64_i8 v[60:63], v[36:39], v[172:175], v[60:63]
	v_mfma_i32_16x16x64_i8 v[44:47], v[36:39], v[204:207], 0
	v_mfma_i32_16x16x64_i8 v[44:47], v[40:43], v[208:211], v[44:47]
	v_mfma_i32_16x16x64_i8 v[12:15], v[40:43], v[220:223], 0
	v_mfma_i32_16x16x64_i8 v[12:15], v[36:39], v[212:215], v[12:15]
	s_setprio 0
	s_setprio 1
	v_mfma_i32_16x16x64_i8 v[24:27], v[140:143], v[204:207], 0
	v_mfma_i32_16x16x64_i8 v[24:27], v[144:147], v[208:211], v[24:27]
	v_mfma_i32_16x16x64_i8 v[8:11], v[144:147], v[220:223], 0
	v_mfma_i32_16x16x64_i8 v[8:11], v[140:143], v[212:215], v[8:11]
	v_mfma_i32_16x16x64_i8 v[28:31], v[140:143], v[164:167], 0
	v_mfma_i32_16x16x64_i8 v[28:31], v[144:147], v[168:171], v[28:31]
	v_mfma_i32_16x16x64_i8 v[36:39], v[144:147], v[176:179], 0
	v_mfma_i32_16x16x64_i8 v[36:39], v[140:143], v[172:175], v[36:39]
	v_mfma_i32_16x16x64_i8 v[20:23], v[156:159], v[204:207], 0
	v_mfma_i32_16x16x64_i8 v[20:23], v[160:163], v[208:211], v[20:23]
	v_mfma_i32_16x16x64_i8 v[4:7], v[160:163], v[220:223], 0
	v_mfma_i32_16x16x64_i8 v[4:7], v[156:159], v[212:215], v[4:7]
	v_mfma_i32_16x16x64_i8 v[32:35], v[156:159], v[164:167], 0
	v_mfma_i32_16x16x64_i8 v[32:35], v[160:163], v[168:171], v[32:35]
	v_mfma_i32_16x16x64_i8 v[40:43], v[160:163], v[176:179], 0
	v_mfma_i32_16x16x64_i8 v[40:43], v[156:159], v[172:175], v[40:43]
	s_setprio 0
	s_barrier
	s_add_i32 s87, 0, 0x18000
	s_add_i32 s96, 0, 0x1c000
	v_add_u32_e32 v72, s87, v217
	v_add_u32_e32 v160, s96, v217
	ds_read_b128 v[52:55], v72
	ds_read_b128 v[56:59], v72 offset:1024
	ds_read_b128 v[68:71], v72 offset:2048
	ds_read_b128 v[72:75], v72 offset:3072
	ds_read_b128 v[140:143], v160
	ds_read_b128 v[144:147], v160 offset:1024
	ds_read_b128 v[156:159], v160 offset:2048
	ds_read_b128 v[160:163], v160 offset:3072
	s_add_u32 s60, s60, 0x80000
	s_addc_u32 s61, s61, 0
	s_mov_b32 m0, s72
	v_lshl_add_u64 v[240:241], s[60:61], 0, v[180:181]
	ds_read_b128 v[164:167], v219 offset:32768
	ds_read_b128 v[168:171], v219 offset:33792
	ds_read_b128 v[172:175], v219 offset:34816
	ds_read_b128 v[176:179], v219 offset:35840
	ds_read_b128 v[204:207], v219 offset:36864
	ds_read_b128 v[208:211], v219 offset:37888
	ds_read_b128 v[212:215], v219 offset:38912
	ds_read_b128 v[220:223], v219 offset:39936
	global_load_lds_dwordx4 v[240:241], off
	v_lshl_add_u64 v[240:241], s[60:61], 0, v[182:183]
	s_mov_b32 m0, s73
	s_nop 0
	global_load_lds_dwordx4 v[240:241], off
	s_waitcnt vmcnt(8)
	s_waitcnt lgkmcnt(0)
	s_barrier
	s_setprio 1
	s_waitcnt lgkmcnt(0)
	v_mfma_i32_16x16x64_i8 v[152:155], v[52:55], v[164:167], v[152:155]
	v_mfma_i32_16x16x64_i8 v[152:155], v[56:59], v[168:171], v[152:155]
	v_mfma_i32_16x16x64_i8 v[128:131], v[56:59], v[176:179], v[128:131]
	v_mfma_i32_16x16x64_i8 v[128:131], v[52:55], v[172:175], v[128:131]
	v_mfma_i32_16x16x64_i8 v[112:115], v[52:55], v[204:207], v[112:115]
	v_mfma_i32_16x16x64_i8 v[112:115], v[56:59], v[208:211], v[112:115]
	v_mfma_i32_16x16x64_i8 v[96:99], v[56:59], v[220:223], v[96:99]
	v_mfma_i32_16x16x64_i8 v[96:99], v[52:55], v[212:215], v[96:99]
	v_mfma_i32_16x16x64_i8 v[148:151], v[68:71], v[164:167], v[148:151]
	v_mfma_i32_16x16x64_i8 v[148:151], v[72:75], v[168:171], v[148:151]
	v_mfma_i32_16x16x64_i8 v[124:127], v[72:75], v[176:179], v[124:127]
	v_mfma_i32_16x16x64_i8 v[124:127], v[68:71], v[172:175], v[124:127]
	v_mfma_i32_16x16x64_i8 v[108:111], v[68:71], v[204:207], v[108:111]
	v_mfma_i32_16x16x64_i8 v[108:111], v[72:75], v[208:211], v[108:111]
	v_mfma_i32_16x16x64_i8 v[92:95], v[72:75], v[220:223], v[92:95]
	v_mfma_i32_16x16x64_i8 v[92:95], v[68:71], v[212:215], v[92:95]
	s_setprio 0
	s_setprio 1
	v_mfma_i32_16x16x64_i8 v[136:139], v[140:143], v[164:167], v[136:139]
	v_mfma_i32_16x16x64_i8 v[136:139], v[144:147], v[168:171], v[136:139]
	v_mfma_i32_16x16x64_i8 v[120:123], v[144:147], v[176:179], v[120:123]
	v_mfma_i32_16x16x64_i8 v[120:123], v[140:143], v[172:175], v[120:123]
	v_mfma_i32_16x16x64_i8 v[104:107], v[140:143], v[204:207], v[104:107]
	v_mfma_i32_16x16x64_i8 v[104:107], v[144:147], v[208:211], v[104:107]
	v_mfma_i32_16x16x64_i8 v[88:91], v[144:147], v[220:223], v[88:91]
	v_mfma_i32_16x16x64_i8 v[88:91], v[140:143], v[212:215], v[88:91]
	v_mfma_i32_16x16x64_i8 v[132:135], v[156:159], v[164:167], v[132:135]
	v_mfma_i32_16x16x64_i8 v[132:135], v[160:163], v[168:171], v[132:135]
	v_mfma_i32_16x16x64_i8 v[116:119], v[160:163], v[176:179], v[116:119]
	v_mfma_i32_16x16x64_i8 v[116:119], v[156:159], v[172:175], v[116:119]
	v_mfma_i32_16x16x64_i8 v[100:103], v[156:159], v[204:207], v[100:103]
	v_mfma_i32_16x16x64_i8 v[100:103], v[160:163], v[208:211], v[100:103]
	v_mfma_i32_16x16x64_i8 v[84:87], v[160:163], v[220:223], v[84:87]
	v_mfma_i32_16x16x64_i8 v[84:87], v[156:159], v[212:215], v[84:87]
	s_setprio 0
	s_barrier
; #define PG8_STAGE(bufoff, gbase, voff) do { _Pragma("unroll") for (int _i = 0; _i < 2; ++_i) \
;         __builtin_amdgcn_global_load_lds((const unsigned*)((const char*)(gbase) + (voff)[_i]), (PG8_LAS unsigned*)(lds + (bufoff) + ldsw + _i * 8192), 16, 0, 0); } while (0)
; #define PG8_LDA(dst, b, h) do { _Pragma("unroll") for (int m = 0; m < 4; ++m) _Pragma("unroll") for (int k = 0; k < 2; ++k) dst[m][k] = *(const PG8_LAS bf16x8*)(lds + PG8_SA(b, h) + aoff + m * 2048 + k * 1024); } while (0)
; #define PG8_WAIT_V(n) asm volatile("s_waitcnt vmcnt(" #n ")" ::: "memory")
; #define PG8_WAIT_L(n) asm volatile("s_waitcnt lgkmcnt(" #n ")" ::: "memory")
; #define PG8_BAR __builtin_amdgcn_s_barrier()
; template <class Epi, class Sched, bool ALIGN_EPI = false, bool SP2 = false, bool I8 = false>
; __device__ __forceinline__ void gemm_phase(PG8_LAS unsigned char* lds, const Gemm g, const Sched& S, const Epi& E) {
;     ...
;         for (int t = 0; t < nt; t += 2) {
;             const bool last = (t == nt - 2);
;             const char* a1 = cA + (size_t)(t + 1) * kstep;
;             const char* a2 = last ? nA : cA + (size_t)(t + 2) * kstep; const char* b2 = last ? nB : cB + (size_t)(t + 2) * kstep;
;             const char* a3 = a2 + kstep; const char* b3 = b2 + kstep;
;             if (last && has_next) S.a_ready(nxt);
;             if constexpr (SP2) {
;             PG8_LDB(B0, 0, 0); PG8_LDB(B1, 0, 1); PG8_SCHED; PG8_LDA(At, 0, 0); PG8_STAGE(PG8_SA(1, 1), a1 + hstep, voffA);
;             PG8_WAIT_V(8); PG8_WAIT_L(0); PG8_BAR; PG8_MMA(0, 0, At, B0); PG8_MMA(0, 1, At, B1); PG8_BAR; PG8_SCHED;
;             PG8_LDA(At, 0, 1); PG8_STAGE(PG8_SB(0, 0), b2, voffB); PG8_STAGE(PG8_SB(0, 1), b2 + hstep, voffB); PG8_STAGE(PG8_SA(0, 0), a2, voffA);
;             PG8_WAIT_V(8); PG8_WAIT_L(0); PG8_BAR; PG8_MMA(1, 0, At, B0); PG8_MMA(1, 1, At, B1); PG8_BAR; PG8_SCHED;
;             PG8_LDB(B0, 1, 0); PG8_LDB(B1, 1, 1); PG8_SCHED; PG8_LDA(At, 1, 0); PG8_STAGE(PG8_SA(0, 1), a2 + hstep, voffA);
;             PG8_WAIT_V(8); PG8_WAIT_L(0); PG8_BAR; PG8_MMA(0, 0, At, B0); PG8_MMA(0, 1, At, B1); PG8_BAR; PG8_SCHED;
;             PG8_LDA(At, 1, 1); PG8_STAGE(PG8_SB(1, 0), b3, voffB); PG8_STAGE(PG8_SB(1, 1), b3 + hstep, voffB); PG8_STAGE(PG8_SA(1, 0), a3, voffA);
;             PG8_WAIT_V(8); PG8_WAIT_L(0); PG8_BAR; PG8_MMA(1, 0, At, B0); PG8_MMA(1, 1, At, B1); PG8_BAR; PG8_SCHED;
	s_add_i32 s60, s87, s46
	v_lshl_add_u64 v[190:191], v[190:191], 0, s[84:85]
	s_mov_b32 m0, s60
	ds_read_b128 v[164:167], v219 offset:49152
	ds_read_b128 v[168:171], v219 offset:50176
	ds_read_b128 v[172:175], v219 offset:51200
	ds_read_b128 v[176:179], v219 offset:52224
	ds_read_b128 v[204:207], v219 offset:53248
	ds_read_b128 v[208:211], v219 offset:54272
	ds_read_b128 v[212:215], v219 offset:55296
	ds_read_b128 v[220:223], v219 offset:56320
	global_load_lds_dwordx4 v[190:191], off
	s_add_i32 m0, s60, 0x2000
	s_add_u32 s58, s58, 0x80080
	v_lshl_add_u64 v[190:191], v[224:225], 0, s[84:85]
	s_addc_u32 s59, s59, 0
	s_add_i32 s60, s96, s46
	global_load_lds_dwordx4 v[190:191], off
	v_lshl_add_u64 v[190:191], s[58:59], 0, v[2:3]
	s_mov_b32 m0, s60
	s_nop 0
	global_load_lds_dwordx4 v[190:191], off
	v_lshl_add_u64 v[190:191], s[58:59], 0, v[184:185]
	s_add_i32 m0, s60, 0x2000
	s_nop 0
	global_load_lds_dwordx4 v[190:191], off
	v_lshl_add_u64 v[190:191], v[226:227], 0, s[84:85]
	s_mov_b32 m0, s28
	s_nop 0
	global_load_lds_dwordx4 v[190:191], off
	v_lshl_add_u64 v[190:191], v[228:229], 0, s[84:85]
	s_mov_b32 m0, s77
	s_nop 0
	global_load_lds_dwordx4 v[190:191], off
	s_waitcnt vmcnt(8)
	s_waitcnt lgkmcnt(0)
	s_barrier
	s_setprio 1
	s_waitcnt lgkmcnt(0)
	v_mfma_i32_16x16x64_i8 v[80:83], v[52:55], v[164:167], v[80:83]
	v_mfma_i32_16x16x64_i8 v[80:83], v[56:59], v[168:171], v[80:83]
	v_mfma_i32_16x16x64_i8 v[64:67], v[56:59], v[176:179], v[64:67]
	v_mfma_i32_16x16x64_i8 v[64:67], v[52:55], v[172:175], v[64:67]
	v_mfma_i32_16x16x64_i8 v[48:51], v[52:55], v[204:207], v[48:51]
	v_mfma_i32_16x16x64_i8 v[48:51], v[56:59], v[208:211], v[48:51]
	v_mfma_i32_16x16x64_i8 v[16:19], v[56:59], v[220:223], v[16:19]
	v_mfma_i32_16x16x64_i8 v[16:19], v[52:55], v[212:215], v[16:19]
	v_mfma_i32_16x16x64_i8 v[76:79], v[68:71], v[164:167], v[76:79]
	v_mfma_i32_16x16x64_i8 v[76:79], v[72:75], v[168:171], v[76:79]
	v_mfma_i32_16x16x64_i8 v[60:63], v[72:75], v[176:179], v[60:63]
	v_mfma_i32_16x16x64_i8 v[60:63], v[68:71], v[172:175], v[60:63]
	v_mfma_i32_16x16x64_i8 v[44:47], v[68:71], v[204:207], v[44:47]
	v_mfma_i32_16x16x64_i8 v[44:47], v[72:75], v[208:211], v[44:47]
	v_mfma_i32_16x16x64_i8 v[12:15], v[72:75], v[220:223], v[12:15]
	v_mfma_i32_16x16x64_i8 v[12:15], v[68:71], v[212:215], v[12:15]
	s_setprio 0
	s_setprio 1
	v_mfma_i32_16x16x64_i8 v[28:31], v[140:143], v[164:167], v[28:31]
	v_mfma_i32_16x16x64_i8 v[72:75], v[144:147], v[168:171], v[28:31]
	v_mfma_i32_16x16x64_i8 v[28:31], v[144:147], v[176:179], v[36:39]
	v_mfma_i32_16x16x64_i8 v[56:59], v[140:143], v[172:175], v[28:31]
	v_mfma_i32_16x16x64_i8 v[24:27], v[140:143], v[204:207], v[24:27]
	v_mfma_i32_16x16x64_i8 v[24:27], v[144:147], v[208:211], v[24:27]
	v_mfma_i32_16x16x64_i8 v[8:11], v[144:147], v[220:223], v[8:11]
	v_mfma_i32_16x16x64_i8 v[8:11], v[140:143], v[212:215], v[8:11]
	v_mfma_i32_16x16x64_i8 v[28:31], v[156:159], v[164:167], v[32:35]
	v_mfma_i32_16x16x64_i8 v[68:71], v[160:163], v[168:171], v[28:31]
	v_mfma_i32_16x16x64_i8 v[28:31], v[160:163], v[176:179], v[40:43]
	v_mfma_i32_16x16x64_i8 v[52:55], v[156:159], v[172:175], v[28:31]
	v_mfma_i32_16x16x64_i8 v[20:23], v[156:159], v[204:207], v[20:23]
	v_mfma_i32_16x16x64_i8 v[20:23], v[160:163], v[208:211], v[20:23]
	v_mfma_i32_16x16x64_i8 v[4:7], v[160:163], v[220:223], v[4:7]
	v_mfma_i32_16x16x64_i8 v[4:7], v[156:159], v[212:215], v[4:7]
	s_setprio 0
	s_barrier
	s_add_i32 s86, s86, 2
	s_add_u32 s54, s54, 0x100
	s_addc_u32 s55, s55, 0
	s_add_u32 s45, s45, 0x100
	s_addc_u32 s49, s49, 0
	s_cmp_gt_u32 s86, 29
	s_cbranch_scc1 .Lkloop_exit_6
.LBB0_1843:
	s_add_u32 s58, s54, 0xfff80080
	s_addc_u32 s59, s55, -1
	s_add_i32 s87, 0, 0x10000
	s_cmp_eq_u32 s86, 28
	s_cselect_b32 s61, s11, s59
	s_cselect_b32 s60, s13, s58
	s_cselect_b32 s59, s34, s49
	s_cselect_b32 s58, s35, s45
	s_add_i32 vcc_lo, 0, 0x14000
	v_add_u32_e32 v40, s87, v217
	v_add_u32_e32 v160, vcc_lo, v217
	ds_read_b128 v[28:31], v40
	ds_read_b128 v[32:35], v40 offset:1024
	ds_read_b128 v[36:39], v40 offset:2048
	ds_read_b128 v[40:43], v40 offset:3072
	ds_read_b128 v[140:143], v160
	ds_read_b128 v[144:147], v160 offset:1024
	ds_read_b128 v[156:159], v160 offset:2048
	ds_read_b128 v[160:163], v160 offset:3072
	v_lshl_add_u64 v[190:191], s[54:55], 0, v[186:187]
	s_add_i32 m0, s65, 0xc000
	ds_read_b128 v[164:167], v219
	ds_read_b128 v[168:171], v219 offset:1024
	ds_read_b128 v[172:175], v219 offset:2048
	ds_read_b128 v[176:179], v219 offset:3072
	ds_read_b128 v[204:207], v219 offset:4096
	ds_read_b128 v[208:211], v219 offset:5120
	ds_read_b128 v[212:215], v219 offset:6144
	ds_read_b128 v[220:223], v219 offset:7168
	global_load_lds_dwordx4 v[190:191], off
	v_lshl_add_u64 v[190:191], s[54:55], 0, v[188:189]
	s_add_i32 m0, s65, 0xe000
	s_nop 0
	global_load_lds_dwordx4 v[190:191], off
	s_waitcnt vmcnt(8)
	s_waitcnt lgkmcnt(0)
	s_barrier
; #define PG8_STAGE(bufoff, gbase, voff) do { _Pragma("unroll") for (int _i = 0; _i < 2; ++_i) \
;         __builtin_amdgcn_global_load_lds((const unsigned*)((const char*)(gbase) + (voff)[_i]), (PG8_LAS unsigned*)(lds + (bufoff) + ldsw + _i * 8192), 16, 0, 0); } while (0)
; #define PG8_LDA(dst, b, h) do { _Pragma("unroll") for (int m = 0; m < 4; ++m) _Pragma("unroll") for (int k = 0; k < 2; ++k) dst[m][k] = *(const PG8_LAS bf16x8*)(lds + PG8_SA(b, h) + aoff + m * 2048 + k * 1024); } while (0)
; #define PG8_WAIT_V(n) asm volatile("s_waitcnt vmcnt(" #n ")" ::: "memory")
; #define PG8_WAIT_L(n) asm volatile("s_waitcnt lgkmcnt(" #n ")" ::: "memory")
; #define PG8_BAR __builtin_amdgcn_s_barrier()
; #define PG8_SCHED __builtin_amdgcn_sched_barrier(0)
; template <class Epi, class Sched, bool ALIGN_EPI = false, bool SP2 = false, bool I8 = false>
; __device__ __forceinline__ void gemm_phase(PG8_LAS unsigned char* lds, const Gemm g, const Sched& S, const Epi& E) {
;     ...
;             PG8_WAIT_V(8); PG8_WAIT_L(0); PG8_BAR; PG8_MMA(0, 0, At, B0); PG8_MMA(0, 1, At, B1); PG8_BAR; PG8_SCHED;
;             PG8_LDA(At, 0, 1); PG8_STAGE(PG8_SB(0, 0), b2, voffB); PG8_STAGE(PG8_SB(0, 1), b2 + hstep, voffB); PG8_STAGE(PG8_SA(0, 0), a2, voffA);
;             PG8_WAIT_V(8); PG8_WAIT_L(0); PG8_BAR; PG8_MMA(1, 0, At, B0); PG8_MMA(1, 1, At, B1); PG8_BAR; PG8_SCHED;
	s_setprio 1
	s_waitcnt lgkmcnt(0)
	v_mfma_i32_16x16x64_i8 v[152:155], v[28:31], v[164:167], v[152:155]
	v_mfma_i32_16x16x64_i8 v[152:155], v[32:35], v[168:171], v[152:155]
	v_mfma_i32_16x16x64_i8 v[128:131], v[32:35], v[176:179], v[128:131]
	v_mfma_i32_16x16x64_i8 v[128:131], v[28:31], v[172:175], v[128:131]
	v_mfma_i32_16x16x64_i8 v[112:115], v[28:31], v[204:207], v[112:115]
	v_mfma_i32_16x16x64_i8 v[112:115], v[32:35], v[208:211], v[112:115]
	v_mfma_i32_16x16x64_i8 v[96:99], v[32:35], v[220:223], v[96:99]
	v_mfma_i32_16x16x64_i8 v[96:99], v[28:31], v[212:215], v[96:99]
	v_mfma_i32_16x16x64_i8 v[148:151], v[36:39], v[164:167], v[148:151]
	v_mfma_i32_16x16x64_i8 v[148:151], v[40:43], v[168:171], v[148:151]
	v_mfma_i32_16x16x64_i8 v[124:127], v[40:43], v[176:179], v[124:127]
	v_mfma_i32_16x16x64_i8 v[124:127], v[36:39], v[172:175], v[124:127]
	v_mfma_i32_16x16x64_i8 v[108:111], v[36:39], v[204:207], v[108:111]
	v_mfma_i32_16x16x64_i8 v[108:111], v[40:43], v[208:211], v[108:111]
	v_mfma_i32_16x16x64_i8 v[92:95], v[40:43], v[220:223], v[92:95]
	v_mfma_i32_16x16x64_i8 v[92:95], v[36:39], v[212:215], v[92:95]
	s_setprio 0
	s_setprio 1
	v_mfma_i32_16x16x64_i8 v[136:139], v[140:143], v[164:167], v[136:139]
	v_mfma_i32_16x16x64_i8 v[136:139], v[144:147], v[168:171], v[136:139]
	v_mfma_i32_16x16x64_i8 v[120:123], v[144:147], v[176:179], v[120:123]
	v_mfma_i32_16x16x64_i8 v[120:123], v[140:143], v[172:175], v[120:123]
	v_mfma_i32_16x16x64_i8 v[104:107], v[140:143], v[204:207], v[104:107]
	v_mfma_i32_16x16x64_i8 v[104:107], v[144:147], v[208:211], v[104:107]
	v_mfma_i32_16x16x64_i8 v[88:91], v[144:147], v[220:223], v[88:91]
	v_mfma_i32_16x16x64_i8 v[88:91], v[140:143], v[212:215], v[88:91]
	v_mfma_i32_16x16x64_i8 v[132:135], v[156:159], v[164:167], v[132:135]
	v_mfma_i32_16x16x64_i8 v[132:135], v[160:163], v[168:171], v[132:135]
	v_mfma_i32_16x16x64_i8 v[116:119], v[160:163], v[176:179], v[116:119]
	v_mfma_i32_16x16x64_i8 v[116:119], v[156:159], v[172:175], v[116:119]
	v_mfma_i32_16x16x64_i8 v[100:103], v[156:159], v[204:207], v[100:103]
	v_mfma_i32_16x16x64_i8 v[100:103], v[160:163], v[208:211], v[100:103]
	v_mfma_i32_16x16x64_i8 v[84:87], v[160:163], v[220:223], v[84:87]
	v_mfma_i32_16x16x64_i8 v[84:87], v[156:159], v[212:215], v[84:87]
	s_setprio 0
	s_barrier
	s_add_i32 s87, s87, s46
	v_lshl_add_u64 v[190:191], s[58:59], 0, v[2:3]
	s_mov_b32 m0, s87
	ds_read_b128 v[164:167], v219 offset:16384
	ds_read_b128 v[168:171], v219 offset:17408
	ds_read_b128 v[172:175], v219 offset:18432
	ds_read_b128 v[176:179], v219 offset:19456
	ds_read_b128 v[204:207], v219 offset:20480
	ds_read_b128 v[208:211], v219 offset:21504
	ds_read_b128 v[212:215], v219 offset:22528
	ds_read_b128 v[220:223], v219 offset:23552
	global_load_lds_dwordx4 v[190:191], off
	s_add_i32 m0, s87, 0x2000
	s_add_u32 s96, s58, 0x80000
	v_lshl_add_u64 v[224:225], s[58:59], 0, v[184:185]
	s_addc_u32 s97, s59, 0
	s_add_i32 s87, vcc_lo, s46
	global_load_lds_dwordx4 v[224:225], off
	v_lshl_add_u64 v[226:227], s[96:97], 0, v[2:3]
	s_mov_b32 m0, s87
	v_lshl_add_u64 v[228:229], s[60:61], 0, v[182:183]
	global_load_lds_dwordx4 v[226:227], off
	v_lshl_add_u64 v[226:227], s[96:97], 0, v[184:185]
	s_add_i32 m0, s87, 0x2000
	s_nop 0
	global_load_lds_dwordx4 v[226:227], off
	v_lshl_add_u64 v[226:227], s[60:61], 0, v[180:181]
	s_mov_b32 m0, s65
	s_nop 0
	global_load_lds_dwordx4 v[226:227], off
	s_mov_b32 m0, s67
	s_nop 0
	global_load_lds_dwordx4 v[228:229], off
	s_waitcnt vmcnt(8)
	s_waitcnt lgkmcnt(0)
	s_barrier
	s_setprio 1
	s_waitcnt lgkmcnt(0)
	v_mfma_i32_16x16x64_i8 v[80:83], v[28:31], v[164:167], v[80:83]
	v_mfma_i32_16x16x64_i8 v[80:83], v[32:35], v[168:171], v[80:83]
	v_mfma_i32_16x16x64_i8 v[64:67], v[32:35], v[176:179], v[64:67]
	v_mfma_i32_16x16x64_i8 v[64:67], v[28:31], v[172:175], v[64:67]
	v_mfma_i32_16x16x64_i8 v[48:51], v[28:31], v[204:207], v[48:51]
	v_mfma_i32_16x16x64_i8 v[48:51], v[32:35], v[208:211], v[48:51]
	v_mfma_i32_16x16x64_i8 v[16:19], v[32:35], v[220:223], v[16:19]
	v_mfma_i32_16x16x64_i8 v[16:19], v[28:31], v[212:215], v[16:19]
	v_mfma_i32_16x16x64_i8 v[76:79], v[36:39], v[164:167], v[76:79]
	v_mfma_i32_16x16x64_i8 v[76:79], v[40:43], v[168:171], v[76:79]
	v_mfma_i32_16x16x64_i8 v[60:63], v[40:43], v[176:179], v[60:63]
	v_mfma_i32_16x16x64_i8 v[60:63], v[36:39], v[172:175], v[60:63]
	v_mfma_i32_16x16x64_i8 v[44:47], v[36:39], v[204:207], v[44:47]
	v_mfma_i32_16x16x64_i8 v[44:47], v[40:43], v[208:211], v[44:47]
	v_mfma_i32_16x16x64_i8 v[12:15], v[40:43], v[220:223], v[12:15]
	v_mfma_i32_16x16x64_i8 v[12:15], v[36:39], v[212:215], v[12:15]
	s_setprio 0
	s_setprio 1
	v_mfma_i32_16x16x64_i8 v[24:27], v[140:143], v[204:207], v[24:27]
	v_mfma_i32_16x16x64_i8 v[24:27], v[144:147], v[208:211], v[24:27]
	v_mfma_i32_16x16x64_i8 v[8:11], v[144:147], v[220:223], v[8:11]
	v_mfma_i32_16x16x64_i8 v[8:11], v[140:143], v[212:215], v[8:11]
	v_mfma_i32_16x16x64_i8 v[28:31], v[140:143], v[164:167], v[72:75]
	v_mfma_i32_16x16x64_i8 v[28:31], v[144:147], v[168:171], v[28:31]
	v_mfma_i32_16x16x64_i8 v[36:39], v[144:147], v[176:179], v[56:59]
	v_mfma_i32_16x16x64_i8 v[36:39], v[140:143], v[172:175], v[36:39]
	v_mfma_i32_16x16x64_i8 v[20:23], v[156:159], v[204:207], v[20:23]
	v_mfma_i32_16x16x64_i8 v[20:23], v[160:163], v[208:211], v[20:23]
	v_mfma_i32_16x16x64_i8 v[4:7], v[160:163], v[220:223], v[4:7]
	v_mfma_i32_16x16x64_i8 v[4:7], v[156:159], v[212:215], v[4:7]
	v_mfma_i32_16x16x64_i8 v[32:35], v[156:159], v[164:167], v[68:71]
	v_mfma_i32_16x16x64_i8 v[32:35], v[160:163], v[168:171], v[32:35]
	v_mfma_i32_16x16x64_i8 v[40:43], v[160:163], v[176:179], v[52:55]
	v_mfma_i32_16x16x64_i8 v[40:43], v[156:159], v[172:175], v[40:43]
	s_setprio 0
	s_barrier
; #define PG8_STAGE(bufoff, gbase, voff) do { _Pragma("unroll") for (int _i = 0; _i < 2; ++_i) \
;         __builtin_amdgcn_global_load_lds((const unsigned*)((const char*)(gbase) + (voff)[_i]), (PG8_LAS unsigned*)(lds + (bufoff) + ldsw + _i * 8192), 16, 0, 0); } while (0)
; #define PG8_LDA(dst, b, h) do { _Pragma("unroll") for (int m = 0; m < 4; ++m) _Pragma("unroll") for (int k = 0; k < 2; ++k) dst[m][k] = *(const PG8_LAS bf16x8*)(lds + PG8_SA(b, h) + aoff + m * 2048 + k * 1024); } while (0)
; #define PG8_LDB(dst, b, h) do { _Pragma("unroll") for (int n = 0; n < 2; ++n) _Pragma("unroll") for (int k = 0; k < 2; ++k) dst[n][k] = *(const PG8_LAS bf16x8*)(lds + PG8_SB(b, h) + boff + n * 2048 + k * 1024); } while (0)
; #define PG8_WAIT_V(n) asm volatile("s_waitcnt vmcnt(" #n ")" ::: "memory")
; #define PG8_WAIT_L(n) asm volatile("s_waitcnt lgkmcnt(" #n ")" ::: "memory")
; #define PG8_BAR __builtin_amdgcn_s_barrier()
; #define PG8_SCHED __builtin_amdgcn_sched_barrier(0)
; template <class Epi, class Sched, bool ALIGN_EPI = false, bool SP2 = false, bool I8 = false>
; __device__ __forceinline__ void gemm_phase(PG8_LAS unsigned char* lds, const Gemm g, const Sched& S, const Epi& E) {
;     ...
;             PG8_LDB(B0, 1, 0); PG8_LDB(B1, 1, 1); PG8_SCHED; PG8_LDA(At, 1, 0); PG8_STAGE(PG8_SA(0, 1), a2 + hstep, voffA);
;             PG8_WAIT_V(8); PG8_WAIT_L(0); PG8_BAR; PG8_MMA(0, 0, At, B0); PG8_MMA(0, 1, At, B1); PG8_BAR; PG8_SCHED;
;             PG8_LDA(At, 1, 1); PG8_STAGE(PG8_SB(1, 0), b3, voffB); PG8_STAGE(PG8_SB(1, 1), b3 + hstep, voffB); PG8_STAGE(PG8_SA(1, 0), a3, voffA);
;             PG8_WAIT_V(8); PG8_WAIT_L(0); PG8_BAR; PG8_MMA(1, 0, At, B0); PG8_MMA(1, 1, At, B1); PG8_BAR; PG8_SCHED;
	s_add_i32 s87, 0, 0x18000
	s_add_i32 s96, 0, 0x1c000
	v_add_u32_e32 v72, s87, v217
	v_add_u32_e32 v160, s96, v217
	ds_read_b128 v[52:55], v72
	ds_read_b128 v[56:59], v72 offset:1024
	ds_read_b128 v[68:71], v72 offset:2048
	ds_read_b128 v[72:75], v72 offset:3072
	ds_read_b128 v[140:143], v160
	ds_read_b128 v[144:147], v160 offset:1024
	ds_read_b128 v[156:159], v160 offset:2048
	ds_read_b128 v[160:163], v160 offset:3072
	s_add_u32 s60, s60, 0x80000
	s_addc_u32 s61, s61, 0
	s_mov_b32 m0, s72
	v_lshl_add_u64 v[240:241], s[60:61], 0, v[180:181]
	ds_read_b128 v[164:167], v219 offset:32768
	ds_read_b128 v[168:171], v219 offset:33792
	ds_read_b128 v[172:175], v219 offset:34816
	ds_read_b128 v[176:179], v219 offset:35840
	ds_read_b128 v[204:207], v219 offset:36864
	ds_read_b128 v[208:211], v219 offset:37888
	ds_read_b128 v[212:215], v219 offset:38912
	ds_read_b128 v[220:223], v219 offset:39936
	global_load_lds_dwordx4 v[240:241], off
	v_lshl_add_u64 v[240:241], s[60:61], 0, v[182:183]
	s_mov_b32 m0, s73
	s_nop 0
	global_load_lds_dwordx4 v[240:241], off
	s_waitcnt vmcnt(8)
	s_waitcnt lgkmcnt(0)
	s_barrier
	s_setprio 1
	s_waitcnt lgkmcnt(0)
	v_mfma_i32_16x16x64_i8 v[152:155], v[52:55], v[164:167], v[152:155]
	v_mfma_i32_16x16x64_i8 v[152:155], v[56:59], v[168:171], v[152:155]
	v_mfma_i32_16x16x64_i8 v[128:131], v[56:59], v[176:179], v[128:131]
	v_mfma_i32_16x16x64_i8 v[128:131], v[52:55], v[172:175], v[128:131]
	v_mfma_i32_16x16x64_i8 v[112:115], v[52:55], v[204:207], v[112:115]
	v_mfma_i32_16x16x64_i8 v[112:115], v[56:59], v[208:211], v[112:115]
	v_mfma_i32_16x16x64_i8 v[96:99], v[56:59], v[220:223], v[96:99]
	v_mfma_i32_16x16x64_i8 v[96:99], v[52:55], v[212:215], v[96:99]
	v_mfma_i32_16x16x64_i8 v[148:151], v[68:71], v[164:167], v[148:151]
	v_mfma_i32_16x16x64_i8 v[148:151], v[72:75], v[168:171], v[148:151]
	v_mfma_i32_16x16x64_i8 v[124:127], v[72:75], v[176:179], v[124:127]
	v_mfma_i32_16x16x64_i8 v[124:127], v[68:71], v[172:175], v[124:127]
	v_mfma_i32_16x16x64_i8 v[108:111], v[68:71], v[204:207], v[108:111]
	v_mfma_i32_16x16x64_i8 v[108:111], v[72:75], v[208:211], v[108:111]
	v_mfma_i32_16x16x64_i8 v[92:95], v[72:75], v[220:223], v[92:95]
	v_mfma_i32_16x16x64_i8 v[92:95], v[68:71], v[212:215], v[92:95]
	s_setprio 0
	s_setprio 1
	v_mfma_i32_16x16x64_i8 v[136:139], v[140:143], v[164:167], v[136:139]
	v_mfma_i32_16x16x64_i8 v[136:139], v[144:147], v[168:171], v[136:139]
	v_mfma_i32_16x16x64_i8 v[120:123], v[144:147], v[176:179], v[120:123]
	v_mfma_i32_16x16x64_i8 v[120:123], v[140:143], v[172:175], v[120:123]
	v_mfma_i32_16x16x64_i8 v[104:107], v[140:143], v[204:207], v[104:107]
	v_mfma_i32_16x16x64_i8 v[104:107], v[144:147], v[208:211], v[104:107]
	v_mfma_i32_16x16x64_i8 v[88:91], v[144:147], v[220:223], v[88:91]
	v_mfma_i32_16x16x64_i8 v[88:91], v[140:143], v[212:215], v[88:91]
	v_mfma_i32_16x16x64_i8 v[132:135], v[156:159], v[164:167], v[132:135]
	v_mfma_i32_16x16x64_i8 v[132:135], v[160:163], v[168:171], v[132:135]
	v_mfma_i32_16x16x64_i8 v[116:119], v[160:163], v[176:179], v[116:119]
	v_mfma_i32_16x16x64_i8 v[116:119], v[156:159], v[172:175], v[116:119]
	v_mfma_i32_16x16x64_i8 v[100:103], v[156:159], v[204:207], v[100:103]
	v_mfma_i32_16x16x64_i8 v[100:103], v[160:163], v[208:211], v[100:103]
	v_mfma_i32_16x16x64_i8 v[84:87], v[160:163], v[220:223], v[84:87]
	v_mfma_i32_16x16x64_i8 v[84:87], v[156:159], v[212:215], v[84:87]
	s_setprio 0
	s_barrier
	s_add_i32 s60, s87, s46
	v_lshl_add_u64 v[190:191], v[190:191], 0, s[84:85]
	s_mov_b32 m0, s60
	ds_read_b128 v[164:167], v219 offset:49152
	ds_read_b128 v[168:171], v219 offset:50176
	ds_read_b128 v[172:175], v219 offset:51200
	ds_read_b128 v[176:179], v219 offset:52224
	ds_read_b128 v[204:207], v219 offset:53248
	ds_read_b128 v[208:211], v219 offset:54272
	ds_read_b128 v[212:215], v219 offset:55296
	ds_read_b128 v[220:223], v219 offset:56320
	global_load_lds_dwordx4 v[190:191], off
	s_add_i32 m0, s60, 0x2000
	s_add_u32 s58, s58, 0x80080
	v_lshl_add_u64 v[190:191], v[224:225], 0, s[84:85]
	s_addc_u32 s59, s59, 0
	s_add_i32 s60, s96, s46
	global_load_lds_dwordx4 v[190:191], off
	v_lshl_add_u64 v[190:191], s[58:59], 0, v[2:3]
	s_mov_b32 m0, s60
	s_nop 0
	global_load_lds_dwordx4 v[190:191], off
	v_lshl_add_u64 v[190:191], s[58:59], 0, v[184:185]
	s_add_i32 m0, s60, 0x2000
	s_nop 0
	global_load_lds_dwordx4 v[190:191], off
	v_lshl_add_u64 v[190:191], v[226:227], 0, s[84:85]
	s_mov_b32 m0, s28
	s_nop 0
	global_load_lds_dwordx4 v[190:191], off
	v_lshl_add_u64 v[190:191], v[228:229], 0, s[84:85]
	s_mov_b32 m0, s77
	s_nop 0
	global_load_lds_dwordx4 v[190:191], off
	s_waitcnt vmcnt(8)
	s_waitcnt lgkmcnt(0)
	s_barrier
	s_setprio 1
	s_waitcnt lgkmcnt(0)
	v_mfma_i32_16x16x64_i8 v[80:83], v[52:55], v[164:167], v[80:83]
	v_mfma_i32_16x16x64_i8 v[80:83], v[56:59], v[168:171], v[80:83]
	v_mfma_i32_16x16x64_i8 v[64:67], v[56:59], v[176:179], v[64:67]
	v_mfma_i32_16x16x64_i8 v[64:67], v[52:55], v[172:175], v[64:67]
	v_mfma_i32_16x16x64_i8 v[48:51], v[52:55], v[204:207], v[48:51]
	v_mfma_i32_16x16x64_i8 v[48:51], v[56:59], v[208:211], v[48:51]
	v_mfma_i32_16x16x64_i8 v[16:19], v[56:59], v[220:223], v[16:19]
	v_mfma_i32_16x16x64_i8 v[16:19], v[52:55], v[212:215], v[16:19]
	v_mfma_i32_16x16x64_i8 v[76:79], v[68:71], v[164:167], v[76:79]
	v_mfma_i32_16x16x64_i8 v[76:79], v[72:75], v[168:171], v[76:79]
	v_mfma_i32_16x16x64_i8 v[60:63], v[72:75], v[176:179], v[60:63]
	v_mfma_i32_16x16x64_i8 v[60:63], v[68:71], v[172:175], v[60:63]
	v_mfma_i32_16x16x64_i8 v[44:47], v[68:71], v[204:207], v[44:47]
	v_mfma_i32_16x16x64_i8 v[44:47], v[72:75], v[208:211], v[44:47]
	v_mfma_i32_16x16x64_i8 v[12:15], v[72:75], v[220:223], v[12:15]
	v_mfma_i32_16x16x64_i8 v[12:15], v[68:71], v[212:215], v[12:15]
	s_setprio 0
	s_setprio 1
	v_mfma_i32_16x16x64_i8 v[28:31], v[140:143], v[164:167], v[28:31]
	v_mfma_i32_16x16x64_i8 v[72:75], v[144:147], v[168:171], v[28:31]
	v_mfma_i32_16x16x64_i8 v[28:31], v[144:147], v[176:179], v[36:39]
	v_mfma_i32_16x16x64_i8 v[56:59], v[140:143], v[172:175], v[28:31]
	v_mfma_i32_16x16x64_i8 v[24:27], v[140:143], v[204:207], v[24:27]
	v_mfma_i32_16x16x64_i8 v[24:27], v[144:147], v[208:211], v[24:27]
	v_mfma_i32_16x16x64_i8 v[8:11], v[144:147], v[220:223], v[8:11]
	v_mfma_i32_16x16x64_i8 v[8:11], v[140:143], v[212:215], v[8:11]
	v_mfma_i32_16x16x64_i8 v[28:31], v[156:159], v[164:167], v[32:35]
	v_mfma_i32_16x16x64_i8 v[68:71], v[160:163], v[168:171], v[28:31]
	v_mfma_i32_16x16x64_i8 v[28:31], v[160:163], v[176:179], v[40:43]
	v_mfma_i32_16x16x64_i8 v[52:55], v[156:159], v[172:175], v[28:31]
	v_mfma_i32_16x16x64_i8 v[20:23], v[156:159], v[204:207], v[20:23]
	v_mfma_i32_16x16x64_i8 v[20:23], v[160:163], v[208:211], v[20:23]
	v_mfma_i32_16x16x64_i8 v[4:7], v[160:163], v[220:223], v[4:7]
	v_mfma_i32_16x16x64_i8 v[4:7], v[156:159], v[212:215], v[4:7]
	s_setprio 0
	s_barrier
	s_add_i32 s86, s86, 2
	s_add_u32 s54, s54, 0x100
	s_addc_u32 s55, s55, 0
	s_add_u32 s45, s45, 0x100
	s_addc_u32 s49, s49, 0
	s_cmp_gt_u32 s86, 29
	s_cbranch_scc0 .LBB0_1843
